# E46: block MFMA order 'snakeB': (bj,n) outer, m boustrophedon (B-fragment-major, neighbours always share A or B), k inner; rest as E30
# baseline (speedup 1.0000x reference)
.Lcm1_skip:
.LBB0_225:
	ds_read_b128 v[128:131], v157
	ds_read_b128 v[132:135], v157 offset:1024
	ds_read_b128 v[146:149], v157 offset:2048
	ds_read_b128 v[164:167], v157 offset:3072
	ds_read_b128 v[168:171], v159
	ds_read_b128 v[172:175], v159 offset:1024
	ds_read_b128 v[176:179], v159 offset:2048
	ds_read_b128 v[180:183], v159 offset:3072
	s_add_u32 s36, s22, 0xfff80080
	s_addc_u32 s37, s23, -1
	s_cmp_eq_u32 s78, 28
	s_cselect_b32 s81, s5, s37
	s_cselect_b32 s80, s14, s36
	s_cselect_b32 vcc_hi, s20, s45
	s_cselect_b32 vcc_lo, s21, s24
	s_add_i32 m0, s77, 0xc000
	ds_read_b128 v[184:187], v161
	ds_read_b128 v[188:191], v161 offset:1024
	ds_read_b128 v[192:195], v161 offset:2048
	ds_read_b128 v[196:199], v161 offset:3072
	ds_read_b128 v[200:203], v161 offset:4096
	ds_read_b128 v[204:207], v161 offset:5120
	ds_read_b128 v[208:211], v161 offset:6144
	ds_read_b128 v[212:215], v161 offset:7168
	global_load_lds_dwordx4 v140, s[22:23]
	s_add_i32 m0, s77, 0xe000
	s_nop 0
	s_add_u32 s98, s22, s6
	s_addc_u32 s99, s23, s7
	global_load_lds_dwordx4 v140, s[98:99]
	s_waitcnt vmcnt(8)
	s_waitcnt lgkmcnt(0)
	s_barrier
	s_setprio 1
	s_waitcnt lgkmcnt(0)
	v_mfma_i32_16x16x64_i8 v[0:3], v[128:131], v[184:187], v[0:3]
	v_mfma_i32_16x16x64_i8 v[0:3], v[132:135], v[188:191], v[0:3]
	v_mfma_i32_16x16x64_i8 v[4:7], v[128:131], v[192:195], v[4:7]
	v_mfma_i32_16x16x64_i8 v[4:7], v[132:135], v[196:199], v[4:7]
	v_mfma_i32_16x16x64_i8 v[12:15], v[128:131], v[200:203], v[12:15]
	v_mfma_i32_16x16x64_i8 v[12:15], v[132:135], v[204:207], v[12:15]
	v_mfma_i32_16x16x64_i8 v[8:11], v[128:131], v[208:211], v[8:11]
	v_mfma_i32_16x16x64_i8 v[8:11], v[132:135], v[212:215], v[8:11]
	v_mfma_i32_16x16x64_i8 v[44:47], v[146:149], v[208:211], v[44:47]
	v_mfma_i32_16x16x64_i8 v[44:47], v[164:167], v[212:215], v[44:47]
	v_mfma_i32_16x16x64_i8 v[48:51], v[146:149], v[200:203], v[48:51]
	v_mfma_i32_16x16x64_i8 v[48:51], v[164:167], v[204:207], v[48:51]
	v_mfma_i32_16x16x64_i8 v[52:55], v[146:149], v[192:195], v[52:55]
	v_mfma_i32_16x16x64_i8 v[52:55], v[164:167], v[196:199], v[52:55]
	v_mfma_i32_16x16x64_i8 v[56:59], v[146:149], v[184:187], v[56:59]
	v_mfma_i32_16x16x64_i8 v[56:59], v[164:167], v[188:191], v[56:59]
	s_setprio 0
	s_setprio 1
	v_mfma_i32_16x16x64_i8 v[88:91], v[168:171], v[184:187], v[88:91]
	v_mfma_i32_16x16x64_i8 v[88:91], v[172:175], v[188:191], v[88:91]
	v_mfma_i32_16x16x64_i8 v[84:87], v[168:171], v[192:195], v[84:87]
	v_mfma_i32_16x16x64_i8 v[84:87], v[172:175], v[196:199], v[84:87]
	v_mfma_i32_16x16x64_i8 v[80:83], v[168:171], v[200:203], v[80:83]
	v_mfma_i32_16x16x64_i8 v[80:83], v[172:175], v[204:207], v[80:83]
	v_mfma_i32_16x16x64_i8 v[76:79], v[168:171], v[208:211], v[76:79]
	v_mfma_i32_16x16x64_i8 v[76:79], v[172:175], v[212:215], v[76:79]
	v_mfma_i32_16x16x64_i8 v[108:111], v[176:179], v[208:211], v[108:111]
	v_mfma_i32_16x16x64_i8 v[108:111], v[180:183], v[212:215], v[108:111]
	v_mfma_i32_16x16x64_i8 v[112:115], v[176:179], v[200:203], v[112:115]
	v_mfma_i32_16x16x64_i8 v[112:115], v[180:183], v[204:207], v[112:115]
	s_setprio 2
	s_barrier
	v_mfma_i32_16x16x64_i8 v[116:119], v[176:179], v[192:195], v[116:119]
	v_mfma_i32_16x16x64_i8 v[116:119], v[180:183], v[196:199], v[116:119]
	v_mfma_i32_16x16x64_i8 v[120:123], v[176:179], v[184:187], v[120:123]
	v_mfma_i32_16x16x64_i8 v[120:123], v[180:183], v[188:191], v[120:123]
	s_setprio 0
	s_add_i32 s36, s86, s63
	s_mov_b32 m0, s36
	ds_read_b128 v[184:187], v161 offset:16384
	ds_read_b128 v[188:191], v161 offset:17408
	ds_read_b128 v[192:195], v161 offset:18432
	ds_read_b128 v[196:199], v161 offset:19456
	ds_read_b128 v[200:203], v161 offset:20480
	ds_read_b128 v[204:207], v161 offset:21504
	ds_read_b128 v[208:211], v161 offset:22528
	ds_read_b128 v[212:215], v161 offset:23552
	global_load_lds_dwordx4 v138, vcc
	s_add_i32 m0, s36, 0x2000
	s_add_i32 s36, s87, s63
	s_add_u32 s98, vcc_lo, s6
	s_addc_u32 s99, vcc_hi, s7
	global_load_lds_dwordx4 v138, s[98:99]
	s_mov_b32 m0, s36
	s_nop 0
	s_add_u32 s98, vcc_lo, s8
	s_addc_u32 s99, vcc_hi, s9
	global_load_lds_dwordx4 v138, s[98:99]
	s_add_i32 m0, s36, 0x2000
	s_nop 0
	s_add_u32 s98, vcc_lo, s10
	s_addc_u32 s99, vcc_hi, s11
	global_load_lds_dwordx4 v138, s[98:99]
	s_mov_b32 m0, s77
	s_nop 0
	global_load_lds_dwordx4 v136, s[80:81]
	s_mov_b32 m0, s97
	s_nop 0
	s_add_u32 s98, s80, s6
	s_addc_u32 s99, s81, s7
	global_load_lds_dwordx4 v136, s[98:99]
	s_waitcnt vmcnt(8)
	s_waitcnt lgkmcnt(0)
	s_barrier
	s_setprio 1
	s_waitcnt lgkmcnt(0)
	v_mfma_i32_16x16x64_i8 v[20:23], v[128:131], v[184:187], v[20:23]
	v_mfma_i32_16x16x64_i8 v[20:23], v[132:135], v[188:191], v[20:23]
	v_mfma_i32_16x16x64_i8 v[16:19], v[128:131], v[192:195], v[16:19]
	v_mfma_i32_16x16x64_i8 v[16:19], v[132:135], v[196:199], v[16:19]
	v_mfma_i32_16x16x64_i8 v[24:27], v[128:131], v[200:203], v[24:27]
	v_mfma_i32_16x16x64_i8 v[24:27], v[132:135], v[204:207], v[24:27]
	v_mfma_i32_16x16x64_i8 v[28:31], v[128:131], v[208:211], v[28:31]
	v_mfma_i32_16x16x64_i8 v[28:31], v[132:135], v[212:215], v[28:31]
	v_mfma_i32_16x16x64_i8 v[60:63], v[146:149], v[208:211], v[60:63]
	v_mfma_i32_16x16x64_i8 v[60:63], v[164:167], v[212:215], v[60:63]
	v_mfma_i32_16x16x64_i8 v[32:35], v[146:149], v[200:203], v[32:35]
	v_mfma_i32_16x16x64_i8 v[32:35], v[164:167], v[204:207], v[32:35]
	v_mfma_i32_16x16x64_i8 v[36:39], v[146:149], v[192:195], v[36:39]
	v_mfma_i32_16x16x64_i8 v[36:39], v[164:167], v[196:199], v[36:39]
	v_mfma_i32_16x16x64_i8 v[40:43], v[146:149], v[184:187], v[40:43]
	v_mfma_i32_16x16x64_i8 v[40:43], v[164:167], v[188:191], v[40:43]
	s_setprio 0
	s_setprio 1
	v_mfma_i32_16x16x64_i8 v[72:75], v[168:171], v[184:187], v[72:75]
	v_mfma_i32_16x16x64_i8 v[72:75], v[172:175], v[188:191], v[72:75]
	v_mfma_i32_16x16x64_i8 v[68:71], v[168:171], v[192:195], v[68:71]
	v_mfma_i32_16x16x64_i8 v[68:71], v[172:175], v[196:199], v[68:71]
	v_mfma_i32_16x16x64_i8 v[64:67], v[168:171], v[200:203], v[64:67]
	v_mfma_i32_16x16x64_i8 v[64:67], v[172:175], v[204:207], v[64:67]
	v_mfma_i32_16x16x64_i8 v[92:95], v[168:171], v[208:211], v[92:95]
	v_mfma_i32_16x16x64_i8 v[92:95], v[172:175], v[212:215], v[92:95]
	v_mfma_i32_16x16x64_i8 v[124:127], v[176:179], v[208:211], v[124:127]
	v_mfma_i32_16x16x64_i8 v[124:127], v[180:183], v[212:215], v[124:127]
	v_mfma_i32_16x16x64_i8 v[96:99], v[176:179], v[200:203], v[96:99]
	v_mfma_i32_16x16x64_i8 v[96:99], v[180:183], v[204:207], v[96:99]
	s_setprio 2
	s_barrier
	v_mfma_i32_16x16x64_i8 v[100:103], v[176:179], v[192:195], v[100:103]
	v_mfma_i32_16x16x64_i8 v[100:103], v[180:183], v[196:199], v[100:103]
	v_mfma_i32_16x16x64_i8 v[104:107], v[176:179], v[184:187], v[104:107]
	v_mfma_i32_16x16x64_i8 v[104:107], v[180:183], v[188:191], v[104:107]
	s_setprio 0
	s_add_i32 s36, 0, 0x18000
	v_add_u32_e32 v152, s36, v153
	s_add_i32 s37, 0, 0x1c000
	ds_read_b128 v[128:131], v152
	ds_read_b128 v[132:135], v152 offset:1024
	ds_read_b128 v[146:149], v152 offset:2048
	ds_read_b128 v[164:167], v152 offset:3072
	v_add_u32_e32 v152, s37, v153
	ds_read_b128 v[168:171], v152
	ds_read_b128 v[172:175], v152 offset:1024
	ds_read_b128 v[176:179], v152 offset:2048
	ds_read_b128 v[180:183], v152 offset:3072
	s_mov_b32 m0, s33
	ds_read_b128 v[184:187], v161 offset:32768
	ds_read_b128 v[188:191], v161 offset:33792
	ds_read_b128 v[192:195], v161 offset:34816
	ds_read_b128 v[196:199], v161 offset:35840
	ds_read_b128 v[200:203], v161 offset:36864
	ds_read_b128 v[204:207], v161 offset:37888
	ds_read_b128 v[208:211], v161 offset:38912
	ds_read_b128 v[212:215], v161 offset:39936
	s_add_u32 s98, s80, s8
	s_addc_u32 s99, s81, s9
	global_load_lds_dwordx4 v136, s[98:99]
	s_mov_b32 m0, s93
	s_nop 0
	s_add_u32 s98, s80, s10
	s_addc_u32 s99, s81, s11
	global_load_lds_dwordx4 v136, s[98:99]
	s_waitcnt vmcnt(8)
	s_waitcnt lgkmcnt(0)
	s_barrier
	s_setprio 1
	s_waitcnt lgkmcnt(0)
	v_mfma_i32_16x16x64_i8 v[0:3], v[128:131], v[184:187], v[0:3]
	v_mfma_i32_16x16x64_i8 v[0:3], v[132:135], v[188:191], v[0:3]
	v_mfma_i32_16x16x64_i8 v[4:7], v[128:131], v[192:195], v[4:7]
	v_mfma_i32_16x16x64_i8 v[4:7], v[132:135], v[196:199], v[4:7]
	v_mfma_i32_16x16x64_i8 v[12:15], v[128:131], v[200:203], v[12:15]
	v_mfma_i32_16x16x64_i8 v[12:15], v[132:135], v[204:207], v[12:15]
	v_mfma_i32_16x16x64_i8 v[8:11], v[128:131], v[208:211], v[8:11]
	v_mfma_i32_16x16x64_i8 v[8:11], v[132:135], v[212:215], v[8:11]
	v_mfma_i32_16x16x64_i8 v[44:47], v[146:149], v[208:211], v[44:47]
	v_mfma_i32_16x16x64_i8 v[44:47], v[164:167], v[212:215], v[44:47]
	v_mfma_i32_16x16x64_i8 v[48:51], v[146:149], v[200:203], v[48:51]
	v_mfma_i32_16x16x64_i8 v[48:51], v[164:167], v[204:207], v[48:51]
	v_mfma_i32_16x16x64_i8 v[52:55], v[146:149], v[192:195], v[52:55]
	v_mfma_i32_16x16x64_i8 v[52:55], v[164:167], v[196:199], v[52:55]
	v_mfma_i32_16x16x64_i8 v[56:59], v[146:149], v[184:187], v[56:59]
	v_mfma_i32_16x16x64_i8 v[56:59], v[164:167], v[188:191], v[56:59]
	s_setprio 0
	s_setprio 1
	v_mfma_i32_16x16x64_i8 v[88:91], v[168:171], v[184:187], v[88:91]
	v_mfma_i32_16x16x64_i8 v[88:91], v[172:175], v[188:191], v[88:91]
	v_mfma_i32_16x16x64_i8 v[84:87], v[168:171], v[192:195], v[84:87]
	v_mfma_i32_16x16x64_i8 v[84:87], v[172:175], v[196:199], v[84:87]
	v_mfma_i32_16x16x64_i8 v[80:83], v[168:171], v[200:203], v[80:83]
	v_mfma_i32_16x16x64_i8 v[80:83], v[172:175], v[204:207], v[80:83]
	v_mfma_i32_16x16x64_i8 v[76:79], v[168:171], v[208:211], v[76:79]
	v_mfma_i32_16x16x64_i8 v[76:79], v[172:175], v[212:215], v[76:79]
	v_mfma_i32_16x16x64_i8 v[108:111], v[176:179], v[208:211], v[108:111]
	v_mfma_i32_16x16x64_i8 v[108:111], v[180:183], v[212:215], v[108:111]
	v_mfma_i32_16x16x64_i8 v[112:115], v[176:179], v[200:203], v[112:115]
	v_mfma_i32_16x16x64_i8 v[112:115], v[180:183], v[204:207], v[112:115]
	s_setprio 2
	s_barrier
	v_mfma_i32_16x16x64_i8 v[116:119], v[176:179], v[192:195], v[116:119]
	v_mfma_i32_16x16x64_i8 v[116:119], v[180:183], v[196:199], v[116:119]
	v_mfma_i32_16x16x64_i8 v[120:123], v[176:179], v[184:187], v[120:123]
	v_mfma_i32_16x16x64_i8 v[120:123], v[180:183], v[188:191], v[120:123]
	s_setprio 0
	s_add_i32 s36, s36, s63
	s_mov_b32 m0, s36
	ds_read_b128 v[184:187], v161 offset:49152
	ds_read_b128 v[188:191], v161 offset:50176
	ds_read_b128 v[192:195], v161 offset:51200
	ds_read_b128 v[196:199], v161 offset:52224
	ds_read_b128 v[200:203], v161 offset:53248
	ds_read_b128 v[204:207], v161 offset:54272
	ds_read_b128 v[208:211], v161 offset:55296
	ds_read_b128 v[212:215], v161 offset:56320
	s_add_u32 s98, vcc_lo, s46
	s_addc_u32 s99, vcc_hi, s47
	global_load_lds_dwordx4 v138, s[98:99]
	s_add_i32 m0, s36, 0x2000
	s_add_i32 s36, s37, s63
	s_add_u32 s98, vcc_lo, s48
	s_addc_u32 s99, vcc_hi, s49
	global_load_lds_dwordx4 v138, s[98:99]
	s_mov_b32 m0, s36
	s_add_u32 s98, vcc_lo, s54
	s_addc_u32 s99, vcc_hi, s55
	global_load_lds_dwordx4 v138, s[98:99]
	s_add_i32 m0, s36, 0x2000
	s_nop 0
	s_add_u32 s98, vcc_lo, s56
	s_addc_u32 s99, vcc_hi, s57
	global_load_lds_dwordx4 v138, s[98:99]
	s_mov_b32 m0, s95
	s_nop 0
	s_add_u32 s98, s80, s46
	s_addc_u32 s99, s81, s47
	global_load_lds_dwordx4 v136, s[98:99]
	s_mov_b32 m0, s82
	s_nop 0
	s_add_u32 s98, s80, s48
	s_addc_u32 s99, s81, s49
	global_load_lds_dwordx4 v136, s[98:99]
	s_waitcnt vmcnt(8)
	s_waitcnt lgkmcnt(0)
	s_barrier
	s_setprio 1
	s_waitcnt lgkmcnt(0)
	v_mfma_i32_16x16x64_i8 v[20:23], v[128:131], v[184:187], v[20:23]
	v_mfma_i32_16x16x64_i8 v[20:23], v[132:135], v[188:191], v[20:23]
	v_mfma_i32_16x16x64_i8 v[16:19], v[128:131], v[192:195], v[16:19]
	v_mfma_i32_16x16x64_i8 v[16:19], v[132:135], v[196:199], v[16:19]
	v_mfma_i32_16x16x64_i8 v[24:27], v[128:131], v[200:203], v[24:27]
	v_mfma_i32_16x16x64_i8 v[24:27], v[132:135], v[204:207], v[24:27]
	v_mfma_i32_16x16x64_i8 v[28:31], v[128:131], v[208:211], v[28:31]
	v_mfma_i32_16x16x64_i8 v[28:31], v[132:135], v[212:215], v[28:31]
	v_mfma_i32_16x16x64_i8 v[60:63], v[146:149], v[208:211], v[60:63]
	v_mfma_i32_16x16x64_i8 v[60:63], v[164:167], v[212:215], v[60:63]
	v_mfma_i32_16x16x64_i8 v[32:35], v[146:149], v[200:203], v[32:35]
	v_mfma_i32_16x16x64_i8 v[32:35], v[164:167], v[204:207], v[32:35]
	v_mfma_i32_16x16x64_i8 v[36:39], v[146:149], v[192:195], v[36:39]
	v_mfma_i32_16x16x64_i8 v[36:39], v[164:167], v[196:199], v[36:39]
	v_mfma_i32_16x16x64_i8 v[40:43], v[146:149], v[184:187], v[40:43]
	v_mfma_i32_16x16x64_i8 v[40:43], v[164:167], v[188:191], v[40:43]
	s_setprio 0
	s_setprio 1
	v_mfma_i32_16x16x64_i8 v[72:75], v[168:171], v[184:187], v[72:75]
	v_mfma_i32_16x16x64_i8 v[72:75], v[172:175], v[188:191], v[72:75]
	v_mfma_i32_16x16x64_i8 v[68:71], v[168:171], v[192:195], v[68:71]
	v_mfma_i32_16x16x64_i8 v[68:71], v[172:175], v[196:199], v[68:71]
	v_mfma_i32_16x16x64_i8 v[64:67], v[168:171], v[200:203], v[64:67]
	v_mfma_i32_16x16x64_i8 v[64:67], v[172:175], v[204:207], v[64:67]
	v_mfma_i32_16x16x64_i8 v[92:95], v[168:171], v[208:211], v[92:95]
	v_mfma_i32_16x16x64_i8 v[92:95], v[172:175], v[212:215], v[92:95]
	v_mfma_i32_16x16x64_i8 v[124:127], v[176:179], v[208:211], v[124:127]
	v_mfma_i32_16x16x64_i8 v[124:127], v[180:183], v[212:215], v[124:127]
	v_mfma_i32_16x16x64_i8 v[96:99], v[176:179], v[200:203], v[96:99]
	v_mfma_i32_16x16x64_i8 v[96:99], v[180:183], v[204:207], v[96:99]
	s_setprio 2
	s_barrier
	v_mfma_i32_16x16x64_i8 v[100:103], v[176:179], v[192:195], v[100:103]
	v_mfma_i32_16x16x64_i8 v[100:103], v[180:183], v[196:199], v[100:103]
	v_mfma_i32_16x16x64_i8 v[104:107], v[176:179], v[184:187], v[104:107]
	v_mfma_i32_16x16x64_i8 v[104:107], v[180:183], v[188:191], v[104:107]
	s_setprio 0
	s_add_i32 s78, s78, 2
	s_add_u32 s24, s24, 0x100
	s_addc_u32 s45, s45, 0
	s_add_u32 s22, s22, 0x100
	s_addc_u32 s23, s23, 0
	s_cmp_gt_u32 s78, 29
	s_cbranch_scc0 .LBB0_225
	v_readlane_b32 s14, v250, 9
	v_readlane_b32 s15, v250, 10
	s_and_b64 vcc, exec, s[14:15]
	s_cbranch_vccz .LBB0_228
	s_barrier

.LBB0_298:
	ds_read_b128 v[128:131], v153
	ds_read_b128 v[132:135], v153 offset:1024
	ds_read_b128 v[146:149], v153 offset:2048
	ds_read_b128 v[158:161], v153 offset:3072
	ds_read_b128 v[162:165], v154
	ds_read_b128 v[166:169], v154 offset:1024
	ds_read_b128 v[170:173], v154 offset:2048
	ds_read_b128 v[174:177], v154 offset:3072
	s_add_u32 s36, s78, 0xfff00080
	s_addc_u32 s37, s79, -1
	s_cmp_eq_u32 s81, 60
	s_cselect_b32 s97, s5, s37
	s_cselect_b32 s96, s14, s36
	s_cselect_b32 vcc_hi, s20, s80
	s_cselect_b32 vcc_lo, s21, s22
	s_add_i32 m0, s33, 0xc000
	ds_read_b128 v[178:181], v155
	ds_read_b128 v[182:185], v155 offset:1024
	ds_read_b128 v[186:189], v155 offset:2048
	ds_read_b128 v[190:193], v155 offset:3072
	ds_read_b128 v[194:197], v155 offset:4096
	ds_read_b128 v[198:201], v155 offset:5120
	ds_read_b128 v[202:205], v155 offset:6144
	ds_read_b128 v[206:209], v155 offset:7168
	global_load_lds_dwordx4 v140, s[78:79]
	s_add_i32 m0, s33, 0xe000
	s_nop 0
	s_add_u32 s98, s78, s0
	s_addc_u32 s99, s79, s1
	global_load_lds_dwordx4 v140, s[98:99]
	s_waitcnt vmcnt(8)
	s_waitcnt lgkmcnt(0)
	s_barrier
	s_setprio 1
	s_waitcnt lgkmcnt(0)
	v_mfma_f32_16x16x32_bf16 v[124:127], v[128:131], v[178:181], v[124:127]
	v_mfma_f32_16x16x32_bf16 v[124:127], v[132:135], v[182:185], v[124:127]
	v_mfma_f32_16x16x32_bf16 v[112:115], v[128:131], v[186:189], v[112:115]
	v_mfma_f32_16x16x32_bf16 v[112:115], v[132:135], v[190:193], v[112:115]
	v_mfma_f32_16x16x32_bf16 v[100:103], v[128:131], v[194:197], v[100:103]
	v_mfma_f32_16x16x32_bf16 v[100:103], v[132:135], v[198:201], v[100:103]
	v_mfma_f32_16x16x32_bf16 v[84:87], v[128:131], v[202:205], v[84:87]
	v_mfma_f32_16x16x32_bf16 v[84:87], v[132:135], v[206:209], v[84:87]
	v_mfma_f32_16x16x32_bf16 v[76:79], v[146:149], v[202:205], v[76:79]
	v_mfma_f32_16x16x32_bf16 v[76:79], v[158:161], v[206:209], v[76:79]
	v_mfma_f32_16x16x32_bf16 v[92:95], v[146:149], v[194:197], v[92:95]
	v_mfma_f32_16x16x32_bf16 v[92:95], v[158:161], v[198:201], v[92:95]
	v_mfma_f32_16x16x32_bf16 v[108:111], v[146:149], v[186:189], v[108:111]
	v_mfma_f32_16x16x32_bf16 v[108:111], v[158:161], v[190:193], v[108:111]
	v_mfma_f32_16x16x32_bf16 v[120:123], v[146:149], v[178:181], v[120:123]
	v_mfma_f32_16x16x32_bf16 v[120:123], v[158:161], v[182:185], v[120:123]
	s_setprio 0
	s_setprio 1
	v_mfma_f32_16x16x32_bf16 v[116:119], v[162:165], v[178:181], v[116:119]
	v_mfma_f32_16x16x32_bf16 v[116:119], v[166:169], v[182:185], v[116:119]
	v_mfma_f32_16x16x32_bf16 v[96:99], v[162:165], v[186:189], v[96:99]
	v_mfma_f32_16x16x32_bf16 v[96:99], v[166:169], v[190:193], v[96:99]
	v_mfma_f32_16x16x32_bf16 v[80:83], v[162:165], v[194:197], v[80:83]
	v_mfma_f32_16x16x32_bf16 v[80:83], v[166:169], v[198:201], v[80:83]
	v_mfma_f32_16x16x32_bf16 v[68:71], v[162:165], v[202:205], v[68:71]
	v_mfma_f32_16x16x32_bf16 v[68:71], v[166:169], v[206:209], v[68:71]
	v_mfma_f32_16x16x32_bf16 v[64:67], v[170:173], v[202:205], v[64:67]
	v_mfma_f32_16x16x32_bf16 v[64:67], v[174:177], v[206:209], v[64:67]
	v_mfma_f32_16x16x32_bf16 v[72:75], v[170:173], v[194:197], v[72:75]
	v_mfma_f32_16x16x32_bf16 v[72:75], v[174:177], v[198:201], v[72:75]
	s_setprio 2
	s_barrier
	v_mfma_f32_16x16x32_bf16 v[88:91], v[170:173], v[186:189], v[88:91]
	v_mfma_f32_16x16x32_bf16 v[88:91], v[174:177], v[190:193], v[88:91]
	v_mfma_f32_16x16x32_bf16 v[104:107], v[170:173], v[178:181], v[104:107]
	v_mfma_f32_16x16x32_bf16 v[104:107], v[174:177], v[182:185], v[104:107]
	s_setprio 0
	s_add_i32 s36, s82, s63
	s_mov_b32 m0, s36
	ds_read_b128 v[178:181], v155 offset:16384
	ds_read_b128 v[182:185], v155 offset:17408
	ds_read_b128 v[186:189], v155 offset:18432
	ds_read_b128 v[190:193], v155 offset:19456
	ds_read_b128 v[194:197], v155 offset:20480
	ds_read_b128 v[198:201], v155 offset:21504
	ds_read_b128 v[202:205], v155 offset:22528
	ds_read_b128 v[206:209], v155 offset:23552
	global_load_lds_dwordx4 v138, vcc
	s_add_i32 m0, s36, 0x2000
	s_add_i32 s36, s83, s63
	s_add_u32 s98, vcc_lo, s0
	s_addc_u32 s99, vcc_hi, s1
	global_load_lds_dwordx4 v138, s[98:99]
	s_mov_b32 m0, s36
	s_nop 0
	s_add_u32 s98, vcc_lo, s6
	s_addc_u32 s99, vcc_hi, s7
	global_load_lds_dwordx4 v138, s[98:99]
	s_add_i32 m0, s36, 0x2000
	s_nop 0
	s_add_u32 s98, vcc_lo, s8
	s_addc_u32 s99, vcc_hi, s9
	global_load_lds_dwordx4 v138, s[98:99]
	s_mov_b32 m0, s33
	s_nop 0
	global_load_lds_dwordx4 v136, s[96:97]
	s_mov_b32 m0, s55
	s_nop 0
	s_add_u32 s98, s96, s0
	s_addc_u32 s99, s97, s1
	global_load_lds_dwordx4 v136, s[98:99]
	s_waitcnt vmcnt(8)
	s_waitcnt lgkmcnt(0)
	s_barrier
	s_setprio 1
	s_waitcnt lgkmcnt(0)
	v_mfma_f32_16x16x32_bf16 v[60:63], v[128:131], v[178:181], v[60:63]
	v_mfma_f32_16x16x32_bf16 v[60:63], v[132:135], v[182:185], v[60:63]
	v_mfma_f32_16x16x32_bf16 v[52:55], v[128:131], v[186:189], v[52:55]
	v_mfma_f32_16x16x32_bf16 v[52:55], v[132:135], v[190:193], v[52:55]
	v_mfma_f32_16x16x32_bf16 v[36:39], v[128:131], v[194:197], v[36:39]
	v_mfma_f32_16x16x32_bf16 v[36:39], v[132:135], v[198:201], v[36:39]
	v_mfma_f32_16x16x32_bf16 v[20:23], v[128:131], v[202:205], v[20:23]
	v_mfma_f32_16x16x32_bf16 v[20:23], v[132:135], v[206:209], v[20:23]
	v_mfma_f32_16x16x32_bf16 v[12:15], v[146:149], v[202:205], v[12:15]
	v_mfma_f32_16x16x32_bf16 v[12:15], v[158:161], v[206:209], v[12:15]
	v_mfma_f32_16x16x32_bf16 v[28:31], v[146:149], v[194:197], v[28:31]
	v_mfma_f32_16x16x32_bf16 v[28:31], v[158:161], v[198:201], v[28:31]
	v_mfma_f32_16x16x32_bf16 v[44:47], v[146:149], v[186:189], v[44:47]
	v_mfma_f32_16x16x32_bf16 v[44:47], v[158:161], v[190:193], v[44:47]
	v_mfma_f32_16x16x32_bf16 v[56:59], v[146:149], v[178:181], v[56:59]
	v_mfma_f32_16x16x32_bf16 v[56:59], v[158:161], v[182:185], v[56:59]
	s_setprio 0
	s_setprio 1
	v_mfma_f32_16x16x32_bf16 v[48:51], v[162:165], v[178:181], v[48:51]
	v_mfma_f32_16x16x32_bf16 v[48:51], v[166:169], v[182:185], v[48:51]
	v_mfma_f32_16x16x32_bf16 v[32:35], v[162:165], v[186:189], v[32:35]
	v_mfma_f32_16x16x32_bf16 v[32:35], v[166:169], v[190:193], v[32:35]
	v_mfma_f32_16x16x32_bf16 v[16:19], v[162:165], v[194:197], v[16:19]
	v_mfma_f32_16x16x32_bf16 v[16:19], v[166:169], v[198:201], v[16:19]
	v_mfma_f32_16x16x32_bf16 v[4:7], v[162:165], v[202:205], v[4:7]
	v_mfma_f32_16x16x32_bf16 v[4:7], v[166:169], v[206:209], v[4:7]
	v_mfma_f32_16x16x32_bf16 v[0:3], v[170:173], v[202:205], v[0:3]
	v_mfma_f32_16x16x32_bf16 v[0:3], v[174:177], v[206:209], v[0:3]
	v_mfma_f32_16x16x32_bf16 v[8:11], v[170:173], v[194:197], v[8:11]
	v_mfma_f32_16x16x32_bf16 v[8:11], v[174:177], v[198:201], v[8:11]
	s_setprio 2
	s_barrier
	v_mfma_f32_16x16x32_bf16 v[24:27], v[170:173], v[186:189], v[24:27]
	v_mfma_f32_16x16x32_bf16 v[24:27], v[174:177], v[190:193], v[24:27]
	v_mfma_f32_16x16x32_bf16 v[40:43], v[170:173], v[178:181], v[40:43]
	v_mfma_f32_16x16x32_bf16 v[40:43], v[174:177], v[182:185], v[40:43]
	s_setprio 0
	s_add_i32 s36, 0, 0x18000
	v_add_u32_e32 v157, s36, v152
	s_add_i32 s37, 0, 0x1c000
	ds_read_b128 v[128:131], v157
	ds_read_b128 v[132:135], v157 offset:1024
	ds_read_b128 v[146:149], v157 offset:2048
	ds_read_b128 v[158:161], v157 offset:3072
	v_add_u32_e32 v157, s37, v152
	ds_read_b128 v[162:165], v157
	ds_read_b128 v[166:169], v157 offset:1024
	ds_read_b128 v[170:173], v157 offset:2048
	ds_read_b128 v[174:177], v157 offset:3072
	s_mov_b32 m0, s57
	ds_read_b128 v[178:181], v155 offset:32768
	ds_read_b128 v[182:185], v155 offset:33792
	ds_read_b128 v[186:189], v155 offset:34816
	ds_read_b128 v[190:193], v155 offset:35840
	ds_read_b128 v[194:197], v155 offset:36864
	ds_read_b128 v[198:201], v155 offset:37888
	ds_read_b128 v[202:205], v155 offset:38912
	ds_read_b128 v[206:209], v155 offset:39936
	s_add_u32 s98, s96, s6
	s_addc_u32 s99, s97, s7
	global_load_lds_dwordx4 v136, s[98:99]
	s_mov_b32 m0, s59
	s_nop 0
	s_add_u32 s98, s96, s8
	s_addc_u32 s99, s97, s9
	global_load_lds_dwordx4 v136, s[98:99]
	s_waitcnt vmcnt(8)
	s_waitcnt lgkmcnt(0)
	s_barrier
	s_setprio 1
	s_waitcnt lgkmcnt(0)
	v_mfma_f32_16x16x32_bf16 v[124:127], v[128:131], v[178:181], v[124:127]
	v_mfma_f32_16x16x32_bf16 v[124:127], v[132:135], v[182:185], v[124:127]
	v_mfma_f32_16x16x32_bf16 v[112:115], v[128:131], v[186:189], v[112:115]
	v_mfma_f32_16x16x32_bf16 v[112:115], v[132:135], v[190:193], v[112:115]
	v_mfma_f32_16x16x32_bf16 v[100:103], v[128:131], v[194:197], v[100:103]
	v_mfma_f32_16x16x32_bf16 v[100:103], v[132:135], v[198:201], v[100:103]
	v_mfma_f32_16x16x32_bf16 v[84:87], v[128:131], v[202:205], v[84:87]
	v_mfma_f32_16x16x32_bf16 v[84:87], v[132:135], v[206:209], v[84:87]
	v_mfma_f32_16x16x32_bf16 v[76:79], v[146:149], v[202:205], v[76:79]
	v_mfma_f32_16x16x32_bf16 v[76:79], v[158:161], v[206:209], v[76:79]
	v_mfma_f32_16x16x32_bf16 v[92:95], v[146:149], v[194:197], v[92:95]
	v_mfma_f32_16x16x32_bf16 v[92:95], v[158:161], v[198:201], v[92:95]
	v_mfma_f32_16x16x32_bf16 v[108:111], v[146:149], v[186:189], v[108:111]
	v_mfma_f32_16x16x32_bf16 v[108:111], v[158:161], v[190:193], v[108:111]
	v_mfma_f32_16x16x32_bf16 v[120:123], v[146:149], v[178:181], v[120:123]
	v_mfma_f32_16x16x32_bf16 v[120:123], v[158:161], v[182:185], v[120:123]
	s_setprio 0
	s_setprio 1
	v_mfma_f32_16x16x32_bf16 v[116:119], v[162:165], v[178:181], v[116:119]
	v_mfma_f32_16x16x32_bf16 v[116:119], v[166:169], v[182:185], v[116:119]
	v_mfma_f32_16x16x32_bf16 v[96:99], v[162:165], v[186:189], v[96:99]
	v_mfma_f32_16x16x32_bf16 v[96:99], v[166:169], v[190:193], v[96:99]
	v_mfma_f32_16x16x32_bf16 v[80:83], v[162:165], v[194:197], v[80:83]
	v_mfma_f32_16x16x32_bf16 v[80:83], v[166:169], v[198:201], v[80:83]
	v_mfma_f32_16x16x32_bf16 v[68:71], v[162:165], v[202:205], v[68:71]
	v_mfma_f32_16x16x32_bf16 v[68:71], v[166:169], v[206:209], v[68:71]
	v_mfma_f32_16x16x32_bf16 v[64:67], v[170:173], v[202:205], v[64:67]
	v_mfma_f32_16x16x32_bf16 v[64:67], v[174:177], v[206:209], v[64:67]
	v_mfma_f32_16x16x32_bf16 v[72:75], v[170:173], v[194:197], v[72:75]
	v_mfma_f32_16x16x32_bf16 v[72:75], v[174:177], v[198:201], v[72:75]
	s_setprio 2
	s_barrier
	v_mfma_f32_16x16x32_bf16 v[88:91], v[170:173], v[186:189], v[88:91]
	v_mfma_f32_16x16x32_bf16 v[88:91], v[174:177], v[190:193], v[88:91]
	v_mfma_f32_16x16x32_bf16 v[104:107], v[170:173], v[178:181], v[104:107]
	v_mfma_f32_16x16x32_bf16 v[104:107], v[174:177], v[182:185], v[104:107]
	s_setprio 0
	s_add_i32 s36, s36, s63
	s_mov_b32 m0, s36
	ds_read_b128 v[178:181], v155 offset:49152
	ds_read_b128 v[182:185], v155 offset:50176
	ds_read_b128 v[186:189], v155 offset:51200
	ds_read_b128 v[190:193], v155 offset:52224
	ds_read_b128 v[194:197], v155 offset:53248
	ds_read_b128 v[198:201], v155 offset:54272
	ds_read_b128 v[202:205], v155 offset:55296
	ds_read_b128 v[206:209], v155 offset:56320
	s_add_u32 s98, vcc_lo, s24
	s_addc_u32 s99, vcc_hi, s25
	global_load_lds_dwordx4 v138, s[98:99]
	s_add_i32 m0, s36, 0x2000
	s_add_i32 s36, s37, s63
	s_add_u32 s98, vcc_lo, s34
	s_addc_u32 s99, vcc_hi, s35
	global_load_lds_dwordx4 v138, s[98:99]
	s_mov_b32 m0, s36
	s_add_u32 s98, vcc_lo, s12
	s_addc_u32 s99, vcc_hi, s13
	global_load_lds_dwordx4 v138, s[98:99]
	s_add_i32 m0, s36, 0x2000
	s_nop 0
	s_add_u32 s98, vcc_lo, s18
	s_addc_u32 s99, vcc_hi, s19
	global_load_lds_dwordx4 v138, s[98:99]
	s_mov_b32 m0, s68
	s_nop 0
	s_add_u32 s98, s96, s24
	s_addc_u32 s99, s97, s25
	global_load_lds_dwordx4 v136, s[98:99]
	s_mov_b32 m0, s69
	s_nop 0
	s_add_u32 s98, s96, s34
	s_addc_u32 s99, s97, s35
	global_load_lds_dwordx4 v136, s[98:99]
	s_waitcnt vmcnt(8)
	s_waitcnt lgkmcnt(0)
	s_barrier
	s_setprio 1
	s_waitcnt lgkmcnt(0)
	v_mfma_f32_16x16x32_bf16 v[60:63], v[128:131], v[178:181], v[60:63]
	v_mfma_f32_16x16x32_bf16 v[60:63], v[132:135], v[182:185], v[60:63]
	v_mfma_f32_16x16x32_bf16 v[52:55], v[128:131], v[186:189], v[52:55]
	v_mfma_f32_16x16x32_bf16 v[52:55], v[132:135], v[190:193], v[52:55]
	v_mfma_f32_16x16x32_bf16 v[36:39], v[128:131], v[194:197], v[36:39]
	v_mfma_f32_16x16x32_bf16 v[36:39], v[132:135], v[198:201], v[36:39]
	v_mfma_f32_16x16x32_bf16 v[20:23], v[128:131], v[202:205], v[20:23]
	v_mfma_f32_16x16x32_bf16 v[20:23], v[132:135], v[206:209], v[20:23]
	v_mfma_f32_16x16x32_bf16 v[12:15], v[146:149], v[202:205], v[12:15]
	v_mfma_f32_16x16x32_bf16 v[12:15], v[158:161], v[206:209], v[12:15]
	v_mfma_f32_16x16x32_bf16 v[28:31], v[146:149], v[194:197], v[28:31]
	v_mfma_f32_16x16x32_bf16 v[28:31], v[158:161], v[198:201], v[28:31]
	v_mfma_f32_16x16x32_bf16 v[44:47], v[146:149], v[186:189], v[44:47]
	v_mfma_f32_16x16x32_bf16 v[44:47], v[158:161], v[190:193], v[44:47]
	v_mfma_f32_16x16x32_bf16 v[56:59], v[146:149], v[178:181], v[56:59]
	v_mfma_f32_16x16x32_bf16 v[56:59], v[158:161], v[182:185], v[56:59]
	s_setprio 0
	s_setprio 1
	v_mfma_f32_16x16x32_bf16 v[48:51], v[162:165], v[178:181], v[48:51]
	v_mfma_f32_16x16x32_bf16 v[48:51], v[166:169], v[182:185], v[48:51]
	v_mfma_f32_16x16x32_bf16 v[32:35], v[162:165], v[186:189], v[32:35]
	v_mfma_f32_16x16x32_bf16 v[32:35], v[166:169], v[190:193], v[32:35]
	v_mfma_f32_16x16x32_bf16 v[16:19], v[162:165], v[194:197], v[16:19]
	v_mfma_f32_16x16x32_bf16 v[16:19], v[166:169], v[198:201], v[16:19]
	v_mfma_f32_16x16x32_bf16 v[4:7], v[162:165], v[202:205], v[4:7]
	v_mfma_f32_16x16x32_bf16 v[4:7], v[166:169], v[206:209], v[4:7]
	v_mfma_f32_16x16x32_bf16 v[0:3], v[170:173], v[202:205], v[0:3]
	v_mfma_f32_16x16x32_bf16 v[0:3], v[174:177], v[206:209], v[0:3]
	v_mfma_f32_16x16x32_bf16 v[8:11], v[170:173], v[194:197], v[8:11]
	v_mfma_f32_16x16x32_bf16 v[8:11], v[174:177], v[198:201], v[8:11]
	s_setprio 2
	s_barrier
	v_mfma_f32_16x16x32_bf16 v[24:27], v[170:173], v[186:189], v[24:27]
	v_mfma_f32_16x16x32_bf16 v[24:27], v[174:177], v[190:193], v[24:27]
	v_mfma_f32_16x16x32_bf16 v[40:43], v[170:173], v[178:181], v[40:43]
	v_mfma_f32_16x16x32_bf16 v[40:43], v[174:177], v[182:185], v[40:43]
	s_setprio 0
	s_add_i32 s81, s81, 2
	s_add_u32 s22, s22, 0x100
	s_addc_u32 s80, s80, 0
	s_add_u32 s78, s78, 0x100
	s_addc_u32 s79, s79, 0
	s_cmp_gt_u32 s81, 61
	s_cbranch_scc0 .LBB0_298
	s_and_b64 vcc, exec, s[26:27]
	s_cbranch_vccz .LBB0_301
	s_barrier

.LBB0_627:
	ds_read_b128 v[128:131], v151
	ds_read_b128 v[142:145], v151 offset:1024
	ds_read_b128 v[146:149], v151 offset:2048
	ds_read_b128 v[154:157], v151 offset:3072
	ds_read_b128 v[158:161], v152
	ds_read_b128 v[162:165], v152 offset:1024
	ds_read_b128 v[166:169], v152 offset:2048
	ds_read_b128 v[170:173], v152 offset:3072
	s_add_u32 s50, s60, 0xfff00080
	s_addc_u32 s51, s61, -1
	s_cmp_eq_u32 s62, 60
	s_cselect_b32 s77, s5, s51
	s_cselect_b32 s76, s49, s50
	s_cselect_b32 s79, s47, s75
	s_cselect_b32 s78, s59, s74
	s_add_i32 m0, s20, 0xc000
	ds_read_b128 v[174:177], v153
	ds_read_b128 v[178:181], v153 offset:1024
	ds_read_b128 v[182:185], v153 offset:2048
	ds_read_b128 v[186:189], v153 offset:3072
	ds_read_b128 v[190:193], v153 offset:4096
	ds_read_b128 v[194:197], v153 offset:5120
	ds_read_b128 v[198:201], v153 offset:6144
	ds_read_b128 v[202:205], v153 offset:7168
	global_load_lds_dwordx4 v136, s[60:61]
	s_add_i32 m0, s20, 0xe000
	s_nop 0
	s_add_u32 s98, s60, s6
	s_addc_u32 s99, s61, s7
	global_load_lds_dwordx4 v136, s[98:99]
	s_waitcnt vmcnt(8)
	s_waitcnt lgkmcnt(0)
	s_barrier
	s_setprio 1
	s_waitcnt lgkmcnt(0)
	v_mfma_f32_16x16x32_bf16 v[124:127], v[128:131], v[174:177], v[124:127]
	v_mfma_f32_16x16x32_bf16 v[124:127], v[142:145], v[178:181], v[124:127]
	v_mfma_f32_16x16x32_bf16 v[116:119], v[128:131], v[182:185], v[116:119]
	v_mfma_f32_16x16x32_bf16 v[116:119], v[142:145], v[186:189], v[116:119]
	v_mfma_f32_16x16x32_bf16 v[108:111], v[128:131], v[190:193], v[108:111]
	v_mfma_f32_16x16x32_bf16 v[108:111], v[142:145], v[194:197], v[108:111]
	v_mfma_f32_16x16x32_bf16 v[100:103], v[128:131], v[198:201], v[100:103]
	v_mfma_f32_16x16x32_bf16 v[100:103], v[142:145], v[202:205], v[100:103]
	v_mfma_f32_16x16x32_bf16 v[96:99], v[146:149], v[198:201], v[96:99]
	v_mfma_f32_16x16x32_bf16 v[96:99], v[154:157], v[202:205], v[96:99]
	v_mfma_f32_16x16x32_bf16 v[104:107], v[146:149], v[190:193], v[104:107]
	v_mfma_f32_16x16x32_bf16 v[104:107], v[154:157], v[194:197], v[104:107]
	v_mfma_f32_16x16x32_bf16 v[112:115], v[146:149], v[182:185], v[112:115]
	v_mfma_f32_16x16x32_bf16 v[112:115], v[154:157], v[186:189], v[112:115]
	v_mfma_f32_16x16x32_bf16 v[120:123], v[146:149], v[174:177], v[120:123]
	v_mfma_f32_16x16x32_bf16 v[120:123], v[154:157], v[178:181], v[120:123]
	s_setprio 0
	s_setprio 1
	v_mfma_f32_16x16x32_bf16 v[92:95], v[158:161], v[174:177], v[92:95]
	v_mfma_f32_16x16x32_bf16 v[92:95], v[162:165], v[178:181], v[92:95]
	v_mfma_f32_16x16x32_bf16 v[84:87], v[158:161], v[182:185], v[84:87]
	v_mfma_f32_16x16x32_bf16 v[84:87], v[162:165], v[186:189], v[84:87]
	v_mfma_f32_16x16x32_bf16 v[76:79], v[158:161], v[190:193], v[76:79]
	v_mfma_f32_16x16x32_bf16 v[76:79], v[162:165], v[194:197], v[76:79]
	v_mfma_f32_16x16x32_bf16 v[68:71], v[158:161], v[198:201], v[68:71]
	v_mfma_f32_16x16x32_bf16 v[68:71], v[162:165], v[202:205], v[68:71]
	v_mfma_f32_16x16x32_bf16 v[64:67], v[166:169], v[198:201], v[64:67]
	v_mfma_f32_16x16x32_bf16 v[64:67], v[170:173], v[202:205], v[64:67]
	v_mfma_f32_16x16x32_bf16 v[72:75], v[166:169], v[190:193], v[72:75]
	v_mfma_f32_16x16x32_bf16 v[72:75], v[170:173], v[194:197], v[72:75]
	s_setprio 2
	s_barrier
	v_mfma_f32_16x16x32_bf16 v[80:83], v[166:169], v[182:185], v[80:83]
	v_mfma_f32_16x16x32_bf16 v[80:83], v[170:173], v[186:189], v[80:83]
	v_mfma_f32_16x16x32_bf16 v[88:91], v[166:169], v[174:177], v[88:91]
	v_mfma_f32_16x16x32_bf16 v[88:91], v[170:173], v[178:181], v[88:91]
	s_setprio 0
	s_add_i32 s50, s72, s14
	s_mov_b32 m0, s50
	ds_read_b128 v[174:177], v153 offset:16384
	ds_read_b128 v[178:181], v153 offset:17408
	ds_read_b128 v[182:185], v153 offset:18432
	ds_read_b128 v[186:189], v153 offset:19456
	ds_read_b128 v[190:193], v153 offset:20480
	ds_read_b128 v[194:197], v153 offset:21504
	ds_read_b128 v[198:201], v153 offset:22528
	ds_read_b128 v[202:205], v153 offset:23552
	global_load_lds_dwordx4 v134, s[78:79]
	s_add_i32 m0, s50, 0x2000
	s_add_i32 s50, s73, s14
	s_add_u32 s98, s78, s6
	s_addc_u32 s99, s79, s7
	global_load_lds_dwordx4 v134, s[98:99]
	s_mov_b32 m0, s50
	s_nop 0
	s_add_u32 s98, s78, s8
	s_addc_u32 s99, s79, s9
	global_load_lds_dwordx4 v134, s[98:99]
	s_add_i32 m0, s50, 0x2000
	s_nop 0
	s_add_u32 s98, s78, s10
	s_addc_u32 s99, s79, s11
	global_load_lds_dwordx4 v134, s[98:99]
	s_mov_b32 m0, s20
	s_nop 0
	global_load_lds_dwordx4 v132, s[76:77]
	s_mov_b32 m0, s21
	s_nop 0
	s_add_u32 s98, s76, s6
	s_addc_u32 s99, s77, s7
	global_load_lds_dwordx4 v132, s[98:99]
	s_waitcnt vmcnt(8)
	s_waitcnt lgkmcnt(0)
	s_barrier
	s_setprio 1
	s_waitcnt lgkmcnt(0)
	v_mfma_f32_16x16x32_bf16 v[60:63], v[128:131], v[174:177], v[60:63]
	v_mfma_f32_16x16x32_bf16 v[60:63], v[142:145], v[178:181], v[60:63]
	v_mfma_f32_16x16x32_bf16 v[52:55], v[128:131], v[182:185], v[52:55]
	v_mfma_f32_16x16x32_bf16 v[52:55], v[142:145], v[186:189], v[52:55]
	v_mfma_f32_16x16x32_bf16 v[44:47], v[128:131], v[190:193], v[44:47]
	v_mfma_f32_16x16x32_bf16 v[44:47], v[142:145], v[194:197], v[44:47]
	v_mfma_f32_16x16x32_bf16 v[36:39], v[128:131], v[198:201], v[36:39]
	v_mfma_f32_16x16x32_bf16 v[36:39], v[142:145], v[202:205], v[36:39]
	v_mfma_f32_16x16x32_bf16 v[32:35], v[146:149], v[198:201], v[32:35]
	v_mfma_f32_16x16x32_bf16 v[32:35], v[154:157], v[202:205], v[32:35]
	v_mfma_f32_16x16x32_bf16 v[40:43], v[146:149], v[190:193], v[40:43]
	v_mfma_f32_16x16x32_bf16 v[40:43], v[154:157], v[194:197], v[40:43]
	v_mfma_f32_16x16x32_bf16 v[48:51], v[146:149], v[182:185], v[48:51]
	v_mfma_f32_16x16x32_bf16 v[48:51], v[154:157], v[186:189], v[48:51]
	v_mfma_f32_16x16x32_bf16 v[56:59], v[146:149], v[174:177], v[56:59]
	v_mfma_f32_16x16x32_bf16 v[56:59], v[154:157], v[178:181], v[56:59]
	s_setprio 0
	s_setprio 1
	v_mfma_f32_16x16x32_bf16 v[28:31], v[158:161], v[174:177], v[28:31]
	v_mfma_f32_16x16x32_bf16 v[28:31], v[162:165], v[178:181], v[28:31]
	v_mfma_f32_16x16x32_bf16 v[20:23], v[158:161], v[182:185], v[20:23]
	v_mfma_f32_16x16x32_bf16 v[20:23], v[162:165], v[186:189], v[20:23]
	v_mfma_f32_16x16x32_bf16 v[12:15], v[158:161], v[190:193], v[12:15]
	v_mfma_f32_16x16x32_bf16 v[12:15], v[162:165], v[194:197], v[12:15]
	v_mfma_f32_16x16x32_bf16 v[4:7], v[158:161], v[198:201], v[4:7]
	v_mfma_f32_16x16x32_bf16 v[4:7], v[162:165], v[202:205], v[4:7]
	v_mfma_f32_16x16x32_bf16 v[0:3], v[166:169], v[198:201], v[0:3]
	v_mfma_f32_16x16x32_bf16 v[0:3], v[170:173], v[202:205], v[0:3]
	v_mfma_f32_16x16x32_bf16 v[8:11], v[166:169], v[190:193], v[8:11]
	v_mfma_f32_16x16x32_bf16 v[8:11], v[170:173], v[194:197], v[8:11]
	s_setprio 2
	s_barrier
	v_mfma_f32_16x16x32_bf16 v[16:19], v[166:169], v[182:185], v[16:19]
	v_mfma_f32_16x16x32_bf16 v[16:19], v[170:173], v[186:189], v[16:19]
	v_mfma_f32_16x16x32_bf16 v[24:27], v[166:169], v[174:177], v[24:27]
	v_mfma_f32_16x16x32_bf16 v[24:27], v[170:173], v[178:181], v[24:27]
	s_setprio 0
	s_add_i32 s50, 0, 0x18000
	s_add_i32 s51, 0, 0x1c000
	v_add_u32_e32 v154, s50, v150
	v_add_u32_e32 v170, s51, v150
	ds_read_b128 v[128:131], v154
	ds_read_b128 v[142:145], v154 offset:1024
	ds_read_b128 v[146:149], v154 offset:2048
	ds_read_b128 v[154:157], v154 offset:3072
	ds_read_b128 v[158:161], v170
	ds_read_b128 v[162:165], v170 offset:1024
	ds_read_b128 v[166:169], v170 offset:2048
	ds_read_b128 v[170:173], v170 offset:3072
	s_mov_b32 m0, s33
	ds_read_b128 v[174:177], v153 offset:32768
	ds_read_b128 v[178:181], v153 offset:33792
	ds_read_b128 v[182:185], v153 offset:34816
	ds_read_b128 v[186:189], v153 offset:35840
	ds_read_b128 v[190:193], v153 offset:36864
	ds_read_b128 v[194:197], v153 offset:37888
	ds_read_b128 v[198:201], v153 offset:38912
	ds_read_b128 v[202:205], v153 offset:39936
	s_add_u32 s98, s76, s8
	s_addc_u32 s99, s77, s9
	global_load_lds_dwordx4 v132, s[98:99]
	s_mov_b32 m0, s64
	s_nop 0
	s_add_u32 s98, s76, s10
	s_addc_u32 s99, s77, s11
	global_load_lds_dwordx4 v132, s[98:99]
	s_waitcnt vmcnt(8)
	s_waitcnt lgkmcnt(0)
	s_barrier
	s_setprio 1
	s_waitcnt lgkmcnt(0)
	v_mfma_f32_16x16x32_bf16 v[124:127], v[128:131], v[174:177], v[124:127]
	v_mfma_f32_16x16x32_bf16 v[124:127], v[142:145], v[178:181], v[124:127]
	v_mfma_f32_16x16x32_bf16 v[116:119], v[128:131], v[182:185], v[116:119]
	v_mfma_f32_16x16x32_bf16 v[116:119], v[142:145], v[186:189], v[116:119]
	v_mfma_f32_16x16x32_bf16 v[108:111], v[128:131], v[190:193], v[108:111]
	v_mfma_f32_16x16x32_bf16 v[108:111], v[142:145], v[194:197], v[108:111]
	v_mfma_f32_16x16x32_bf16 v[100:103], v[128:131], v[198:201], v[100:103]
	v_mfma_f32_16x16x32_bf16 v[100:103], v[142:145], v[202:205], v[100:103]
	v_mfma_f32_16x16x32_bf16 v[96:99], v[146:149], v[198:201], v[96:99]
	v_mfma_f32_16x16x32_bf16 v[96:99], v[154:157], v[202:205], v[96:99]
	v_mfma_f32_16x16x32_bf16 v[104:107], v[146:149], v[190:193], v[104:107]
	v_mfma_f32_16x16x32_bf16 v[104:107], v[154:157], v[194:197], v[104:107]
	v_mfma_f32_16x16x32_bf16 v[112:115], v[146:149], v[182:185], v[112:115]
	v_mfma_f32_16x16x32_bf16 v[112:115], v[154:157], v[186:189], v[112:115]
	v_mfma_f32_16x16x32_bf16 v[120:123], v[146:149], v[174:177], v[120:123]
	v_mfma_f32_16x16x32_bf16 v[120:123], v[154:157], v[178:181], v[120:123]
	s_setprio 0
	s_setprio 1
	v_mfma_f32_16x16x32_bf16 v[92:95], v[158:161], v[174:177], v[92:95]
	v_mfma_f32_16x16x32_bf16 v[92:95], v[162:165], v[178:181], v[92:95]
	v_mfma_f32_16x16x32_bf16 v[84:87], v[158:161], v[182:185], v[84:87]
	v_mfma_f32_16x16x32_bf16 v[84:87], v[162:165], v[186:189], v[84:87]
	v_mfma_f32_16x16x32_bf16 v[76:79], v[158:161], v[190:193], v[76:79]
	v_mfma_f32_16x16x32_bf16 v[76:79], v[162:165], v[194:197], v[76:79]
	v_mfma_f32_16x16x32_bf16 v[68:71], v[158:161], v[198:201], v[68:71]
	v_mfma_f32_16x16x32_bf16 v[68:71], v[162:165], v[202:205], v[68:71]
	v_mfma_f32_16x16x32_bf16 v[64:67], v[166:169], v[198:201], v[64:67]
	v_mfma_f32_16x16x32_bf16 v[64:67], v[170:173], v[202:205], v[64:67]
	v_mfma_f32_16x16x32_bf16 v[72:75], v[166:169], v[190:193], v[72:75]
	v_mfma_f32_16x16x32_bf16 v[72:75], v[170:173], v[194:197], v[72:75]
	s_setprio 2
	s_barrier
	v_mfma_f32_16x16x32_bf16 v[80:83], v[166:169], v[182:185], v[80:83]
	v_mfma_f32_16x16x32_bf16 v[80:83], v[170:173], v[186:189], v[80:83]
	v_mfma_f32_16x16x32_bf16 v[88:91], v[166:169], v[174:177], v[88:91]
	v_mfma_f32_16x16x32_bf16 v[88:91], v[170:173], v[178:181], v[88:91]
	s_setprio 0
	s_add_i32 s50, s50, s14
	s_mov_b32 m0, s50
	ds_read_b128 v[174:177], v153 offset:49152
	ds_read_b128 v[178:181], v153 offset:50176
	ds_read_b128 v[182:185], v153 offset:51200
	ds_read_b128 v[186:189], v153 offset:52224
	ds_read_b128 v[190:193], v153 offset:53248
	ds_read_b128 v[194:197], v153 offset:54272
	ds_read_b128 v[198:201], v153 offset:55296
	ds_read_b128 v[202:205], v153 offset:56320
	s_add_u32 s98, s78, s24
	s_addc_u32 s99, s79, s25
	global_load_lds_dwordx4 v134, s[98:99]
	s_add_i32 m0, s50, 0x2000
	s_add_i32 s50, s51, s14
	s_add_u32 s98, s78, s34
	s_addc_u32 s99, s79, s35
	global_load_lds_dwordx4 v134, s[98:99]
	s_mov_b32 m0, s50
	s_add_u32 s98, s78, s36
	s_addc_u32 s99, s79, s37
	global_load_lds_dwordx4 v134, s[98:99]
	s_add_i32 m0, s50, 0x2000
	s_nop 0
	s_add_u32 s98, s78, s38
	s_addc_u32 s99, s79, s39
	global_load_lds_dwordx4 v134, s[98:99]
	s_mov_b32 m0, s66
	s_nop 0
	s_add_u32 s98, s76, s24
	s_addc_u32 s99, s77, s25
	global_load_lds_dwordx4 v132, s[98:99]
	s_mov_b32 m0, s67
	s_nop 0
	s_add_u32 s98, s76, s34
	s_addc_u32 s99, s77, s35
	global_load_lds_dwordx4 v132, s[98:99]
	s_waitcnt vmcnt(8)
	s_waitcnt lgkmcnt(0)
	s_barrier
	s_setprio 1
	s_waitcnt lgkmcnt(0)
	v_mfma_f32_16x16x32_bf16 v[60:63], v[128:131], v[174:177], v[60:63]
	v_mfma_f32_16x16x32_bf16 v[60:63], v[142:145], v[178:181], v[60:63]
	v_mfma_f32_16x16x32_bf16 v[52:55], v[128:131], v[182:185], v[52:55]
	v_mfma_f32_16x16x32_bf16 v[52:55], v[142:145], v[186:189], v[52:55]
	v_mfma_f32_16x16x32_bf16 v[44:47], v[128:131], v[190:193], v[44:47]
	v_mfma_f32_16x16x32_bf16 v[44:47], v[142:145], v[194:197], v[44:47]
	v_mfma_f32_16x16x32_bf16 v[36:39], v[128:131], v[198:201], v[36:39]
	v_mfma_f32_16x16x32_bf16 v[36:39], v[142:145], v[202:205], v[36:39]
	v_mfma_f32_16x16x32_bf16 v[32:35], v[146:149], v[198:201], v[32:35]
	v_mfma_f32_16x16x32_bf16 v[32:35], v[154:157], v[202:205], v[32:35]
	v_mfma_f32_16x16x32_bf16 v[40:43], v[146:149], v[190:193], v[40:43]
	v_mfma_f32_16x16x32_bf16 v[40:43], v[154:157], v[194:197], v[40:43]
	v_mfma_f32_16x16x32_bf16 v[48:51], v[146:149], v[182:185], v[48:51]
	v_mfma_f32_16x16x32_bf16 v[48:51], v[154:157], v[186:189], v[48:51]
	v_mfma_f32_16x16x32_bf16 v[56:59], v[146:149], v[174:177], v[56:59]
	v_mfma_f32_16x16x32_bf16 v[56:59], v[154:157], v[178:181], v[56:59]
	s_setprio 0
	s_setprio 1
	v_mfma_f32_16x16x32_bf16 v[28:31], v[158:161], v[174:177], v[28:31]
	v_mfma_f32_16x16x32_bf16 v[28:31], v[162:165], v[178:181], v[28:31]
	v_mfma_f32_16x16x32_bf16 v[20:23], v[158:161], v[182:185], v[20:23]
	v_mfma_f32_16x16x32_bf16 v[20:23], v[162:165], v[186:189], v[20:23]
	v_mfma_f32_16x16x32_bf16 v[12:15], v[158:161], v[190:193], v[12:15]
	v_mfma_f32_16x16x32_bf16 v[12:15], v[162:165], v[194:197], v[12:15]
	v_mfma_f32_16x16x32_bf16 v[4:7], v[158:161], v[198:201], v[4:7]
	v_mfma_f32_16x16x32_bf16 v[4:7], v[162:165], v[202:205], v[4:7]
	v_mfma_f32_16x16x32_bf16 v[0:3], v[166:169], v[198:201], v[0:3]
	v_mfma_f32_16x16x32_bf16 v[0:3], v[170:173], v[202:205], v[0:3]
	v_mfma_f32_16x16x32_bf16 v[8:11], v[166:169], v[190:193], v[8:11]
	v_mfma_f32_16x16x32_bf16 v[8:11], v[170:173], v[194:197], v[8:11]
	s_setprio 2
	s_barrier
	v_mfma_f32_16x16x32_bf16 v[16:19], v[166:169], v[182:185], v[16:19]
	v_mfma_f32_16x16x32_bf16 v[16:19], v[170:173], v[186:189], v[16:19]
	v_mfma_f32_16x16x32_bf16 v[24:27], v[166:169], v[174:177], v[24:27]
	v_mfma_f32_16x16x32_bf16 v[24:27], v[170:173], v[178:181], v[24:27]
	s_setprio 0
	s_add_i32 s62, s62, 2
	s_add_u32 s74, s74, 0x100
	s_addc_u32 s75, s75, 0
	s_add_u32 s60, s60, 0x100
	s_addc_u32 s61, s61, 0
	s_cmp_gt_u32 s62, 61
	s_cbranch_scc0 .LBB0_627
	s_and_b64 vcc, exec, s[40:41]
	s_cbranch_vccz .LBB0_630
	s_barrier

.Lcm4_skip:
.LBB0_800:
	ds_read_b128 v[128:131], v187
	ds_read_b128 v[132:135], v187 offset:1024
	ds_read_b128 v[136:139], v187 offset:2048
	ds_read_b128 v[140:143], v187 offset:3072
	ds_read_b128 v[144:147], v188
	ds_read_b128 v[148:151], v188 offset:1024
	ds_read_b128 v[152:155], v188 offset:2048
	ds_read_b128 v[156:159], v188 offset:3072
	s_add_u32 s9, s6, 0xfff80080
	s_addc_u32 s50, s7, -1
	s_cmp_eq_u32 s8, 28
	s_cselect_b32 vcc_hi, s5, s50
	s_cselect_b32 vcc_lo, s10, s9
	s_cselect_b32 s51, s11, s78
	s_cselect_b32 s50, s73, s75
	s_add_i32 m0, s65, 0xc000
	ds_read_b128 v[160:163], v189
	ds_read_b128 v[164:167], v189 offset:1024
	ds_read_b128 v[168:171], v189 offset:2048
	ds_read_b128 v[192:195], v189 offset:3072
	ds_read_b128 v[196:199], v189 offset:4096
	ds_read_b128 v[200:203], v189 offset:5120
	ds_read_b128 v[204:207], v189 offset:6144
	ds_read_b128 v[208:211], v189 offset:7168
	global_load_lds_dwordx4 v178, s[6:7]
	s_add_i32 m0, s65, 0xe000
	s_nop 0
	s_add_u32 s98, s6, s36
	s_addc_u32 s99, s7, s37
	global_load_lds_dwordx4 v178, s[98:99]
	s_waitcnt vmcnt(8)
	s_waitcnt lgkmcnt(0)
	s_barrier
	s_setprio 1
	s_waitcnt lgkmcnt(0)
	v_mfma_i32_16x16x64_i8 v[84:87], v[128:131], v[160:163], v[84:87]
	v_mfma_i32_16x16x64_i8 v[84:87], v[132:135], v[164:167], v[84:87]
	v_mfma_i32_16x16x64_i8 v[88:91], v[128:131], v[168:171], v[88:91]
	v_mfma_i32_16x16x64_i8 v[88:91], v[132:135], v[192:195], v[88:91]
	v_mfma_i32_16x16x64_i8 v[92:95], v[128:131], v[196:199], v[92:95]
	v_mfma_i32_16x16x64_i8 v[92:95], v[132:135], v[200:203], v[92:95]
	v_mfma_i32_16x16x64_i8 v[96:99], v[128:131], v[204:207], v[96:99]
	v_mfma_i32_16x16x64_i8 v[96:99], v[132:135], v[208:211], v[96:99]
	v_mfma_i32_16x16x64_i8 v[28:31], v[136:139], v[204:207], v[28:31]
	v_mfma_i32_16x16x64_i8 v[28:31], v[140:143], v[208:211], v[28:31]
	v_mfma_i32_16x16x64_i8 v[24:27], v[136:139], v[196:199], v[24:27]
	v_mfma_i32_16x16x64_i8 v[24:27], v[140:143], v[200:203], v[24:27]
	v_mfma_i32_16x16x64_i8 v[20:23], v[136:139], v[168:171], v[20:23]
	v_mfma_i32_16x16x64_i8 v[20:23], v[140:143], v[192:195], v[20:23]
	v_mfma_i32_16x16x64_i8 v[16:19], v[136:139], v[160:163], v[16:19]
	v_mfma_i32_16x16x64_i8 v[16:19], v[140:143], v[164:167], v[16:19]
	s_setprio 0
	s_setprio 1
	v_mfma_i32_16x16x64_i8 v[124:127], v[144:147], v[160:163], v[124:127]
	v_mfma_i32_16x16x64_i8 v[124:127], v[148:151], v[164:167], v[124:127]
	v_mfma_i32_16x16x64_i8 v[120:123], v[144:147], v[168:171], v[120:123]
	v_mfma_i32_16x16x64_i8 v[120:123], v[148:151], v[192:195], v[120:123]
	v_mfma_i32_16x16x64_i8 v[116:119], v[144:147], v[196:199], v[116:119]
	v_mfma_i32_16x16x64_i8 v[116:119], v[148:151], v[200:203], v[116:119]
	v_mfma_i32_16x16x64_i8 v[112:115], v[144:147], v[204:207], v[112:115]
	v_mfma_i32_16x16x64_i8 v[112:115], v[148:151], v[208:211], v[112:115]
	v_mfma_i32_16x16x64_i8 v[60:63], v[152:155], v[204:207], v[60:63]
	v_mfma_i32_16x16x64_i8 v[60:63], v[156:159], v[208:211], v[60:63]
	v_mfma_i32_16x16x64_i8 v[80:83], v[152:155], v[196:199], v[80:83]
	v_mfma_i32_16x16x64_i8 v[80:83], v[156:159], v[200:203], v[80:83]
	s_setprio 2
	s_barrier
	v_mfma_i32_16x16x64_i8 v[72:75], v[152:155], v[168:171], v[72:75]
	v_mfma_i32_16x16x64_i8 v[72:75], v[156:159], v[192:195], v[72:75]
	v_mfma_i32_16x16x64_i8 v[68:71], v[152:155], v[160:163], v[68:71]
	v_mfma_i32_16x16x64_i8 v[68:71], v[156:159], v[164:167], v[68:71]
	s_setprio 0
	s_add_i32 s9, s80, s33
	s_mov_b64 s[100:101], s[50:51]
	s_mov_b32 m0, s9
	ds_read_b128 v[160:163], v189 offset:16384
	ds_read_b128 v[164:167], v189 offset:17408
	ds_read_b128 v[168:171], v189 offset:18432
	ds_read_b128 v[192:195], v189 offset:19456
	ds_read_b128 v[196:199], v189 offset:20480
	ds_read_b128 v[200:203], v189 offset:21504
	ds_read_b128 v[204:207], v189 offset:22528
	ds_read_b128 v[208:211], v189 offset:23552
	global_load_lds_dwordx4 v174, s[50:51]
	s_add_i32 m0, s9, 0x2000
	s_add_i32 s9, s81, s33
	s_add_u32 s98, s50, s36
	s_addc_u32 s99, s51, s37
	global_load_lds_dwordx4 v174, s[98:99]
	s_mov_b32 m0, s9
	s_nop 0
	s_add_u32 s98, s50, s38
	s_addc_u32 s99, s51, s39
	global_load_lds_dwordx4 v174, s[98:99]
	s_add_i32 m0, s9, 0x2000
	s_nop 0
	s_add_u32 s98, s50, s40
	s_addc_u32 s99, s51, s41
	global_load_lds_dwordx4 v174, s[98:99]
	s_mov_b32 m0, s65
	s_nop 0
	global_load_lds_dwordx4 v172, vcc
	s_mov_b32 m0, s67
	s_nop 0
	s_add_u32 s98, vcc_lo, s36
	s_addc_u32 s99, vcc_hi, s37
	global_load_lds_dwordx4 v172, s[98:99]
	s_waitcnt vmcnt(8)
	s_waitcnt lgkmcnt(0)
	s_barrier
	s_setprio 1
	s_waitcnt lgkmcnt(0)
	v_mfma_i32_16x16x64_i8 v[48:51], v[128:131], v[160:163], v[48:51]
	v_mfma_i32_16x16x64_i8 v[48:51], v[132:135], v[164:167], v[48:51]
	v_mfma_i32_16x16x64_i8 v[52:55], v[128:131], v[168:171], v[52:55]
	v_mfma_i32_16x16x64_i8 v[52:55], v[132:135], v[192:195], v[52:55]
	v_mfma_i32_16x16x64_i8 v[56:59], v[128:131], v[196:199], v[56:59]
	v_mfma_i32_16x16x64_i8 v[56:59], v[132:135], v[200:203], v[56:59]
	v_mfma_i32_16x16x64_i8 v[64:67], v[128:131], v[204:207], v[64:67]
	v_mfma_i32_16x16x64_i8 v[64:67], v[132:135], v[208:211], v[64:67]
	v_mfma_i32_16x16x64_i8 v[12:15], v[136:139], v[204:207], v[12:15]
	v_mfma_i32_16x16x64_i8 v[12:15], v[140:143], v[208:211], v[12:15]
	v_mfma_i32_16x16x64_i8 v[8:11], v[136:139], v[196:199], v[8:11]
	v_mfma_i32_16x16x64_i8 v[8:11], v[140:143], v[200:203], v[8:11]
	v_mfma_i32_16x16x64_i8 v[4:7], v[136:139], v[168:171], v[4:7]
	v_mfma_i32_16x16x64_i8 v[4:7], v[140:143], v[192:195], v[4:7]
	v_mfma_i32_16x16x64_i8 v[0:3], v[136:139], v[160:163], v[0:3]
	v_mfma_i32_16x16x64_i8 v[0:3], v[140:143], v[164:167], v[0:3]
	s_setprio 0
	s_setprio 1
	v_mfma_i32_16x16x64_i8 v[108:111], v[144:147], v[160:163], v[108:111]
	v_mfma_i32_16x16x64_i8 v[108:111], v[148:151], v[164:167], v[108:111]
	v_mfma_i32_16x16x64_i8 v[104:107], v[144:147], v[168:171], v[104:107]
	v_mfma_i32_16x16x64_i8 v[104:107], v[148:151], v[192:195], v[104:107]
	v_mfma_i32_16x16x64_i8 v[100:103], v[144:147], v[196:199], v[100:103]
	v_mfma_i32_16x16x64_i8 v[100:103], v[148:151], v[200:203], v[100:103]
	v_mfma_i32_16x16x64_i8 v[76:79], v[144:147], v[204:207], v[76:79]
	v_mfma_i32_16x16x64_i8 v[76:79], v[148:151], v[208:211], v[76:79]
	v_mfma_i32_16x16x64_i8 v[36:39], v[152:155], v[204:207], v[36:39]
	v_mfma_i32_16x16x64_i8 v[36:39], v[156:159], v[208:211], v[36:39]
	v_mfma_i32_16x16x64_i8 v[32:35], v[152:155], v[196:199], v[32:35]
	v_mfma_i32_16x16x64_i8 v[32:35], v[156:159], v[200:203], v[32:35]
	s_setprio 2
	s_barrier
	v_mfma_i32_16x16x64_i8 v[40:43], v[152:155], v[168:171], v[40:43]
	v_mfma_i32_16x16x64_i8 v[40:43], v[156:159], v[192:195], v[40:43]
	v_mfma_i32_16x16x64_i8 v[44:47], v[152:155], v[160:163], v[44:47]
	v_mfma_i32_16x16x64_i8 v[44:47], v[156:159], v[164:167], v[44:47]
	s_setprio 0
	s_add_i32 s9, 0, 0x18000
	s_add_i32 s50, 0, 0x1c000
	v_add_u32_e32 v140, s9, v186
	v_add_u32_e32 v156, s50, v186
	ds_read_b128 v[128:131], v140
	ds_read_b128 v[132:135], v140 offset:1024
	ds_read_b128 v[136:139], v140 offset:2048
	ds_read_b128 v[140:143], v140 offset:3072
	ds_read_b128 v[144:147], v156
	ds_read_b128 v[148:151], v156 offset:1024
	ds_read_b128 v[152:155], v156 offset:2048
	ds_read_b128 v[156:159], v156 offset:3072
	s_mov_b32 m0, s71
	ds_read_b128 v[160:163], v189 offset:32768
	ds_read_b128 v[164:167], v189 offset:33792
	ds_read_b128 v[168:171], v189 offset:34816
	ds_read_b128 v[192:195], v189 offset:35840
	ds_read_b128 v[196:199], v189 offset:36864
	ds_read_b128 v[200:203], v189 offset:37888
	ds_read_b128 v[204:207], v189 offset:38912
	ds_read_b128 v[208:211], v189 offset:39936
	s_add_u32 s98, vcc_lo, s38
	s_addc_u32 s99, vcc_hi, s39
	global_load_lds_dwordx4 v172, s[98:99]
	s_mov_b32 m0, s82
	s_nop 0
	s_add_u32 s98, vcc_lo, s40
	s_addc_u32 s99, vcc_hi, s41
	global_load_lds_dwordx4 v172, s[98:99]
	s_waitcnt vmcnt(8)
	s_waitcnt lgkmcnt(0)
	s_barrier
	s_setprio 1
	s_waitcnt lgkmcnt(0)
	v_mfma_i32_16x16x64_i8 v[84:87], v[128:131], v[160:163], v[84:87]
	v_mfma_i32_16x16x64_i8 v[84:87], v[132:135], v[164:167], v[84:87]
	v_mfma_i32_16x16x64_i8 v[88:91], v[128:131], v[168:171], v[88:91]
	v_mfma_i32_16x16x64_i8 v[88:91], v[132:135], v[192:195], v[88:91]
	v_mfma_i32_16x16x64_i8 v[92:95], v[128:131], v[196:199], v[92:95]
	v_mfma_i32_16x16x64_i8 v[92:95], v[132:135], v[200:203], v[92:95]
	v_mfma_i32_16x16x64_i8 v[96:99], v[128:131], v[204:207], v[96:99]
	v_mfma_i32_16x16x64_i8 v[96:99], v[132:135], v[208:211], v[96:99]
	v_mfma_i32_16x16x64_i8 v[28:31], v[136:139], v[204:207], v[28:31]
	v_mfma_i32_16x16x64_i8 v[28:31], v[140:143], v[208:211], v[28:31]
	v_mfma_i32_16x16x64_i8 v[24:27], v[136:139], v[196:199], v[24:27]
	v_mfma_i32_16x16x64_i8 v[24:27], v[140:143], v[200:203], v[24:27]
	v_mfma_i32_16x16x64_i8 v[20:23], v[136:139], v[168:171], v[20:23]
	v_mfma_i32_16x16x64_i8 v[20:23], v[140:143], v[192:195], v[20:23]
	v_mfma_i32_16x16x64_i8 v[16:19], v[136:139], v[160:163], v[16:19]
	v_mfma_i32_16x16x64_i8 v[16:19], v[140:143], v[164:167], v[16:19]
	s_setprio 0
	s_setprio 1
	v_mfma_i32_16x16x64_i8 v[124:127], v[144:147], v[160:163], v[124:127]
	v_mfma_i32_16x16x64_i8 v[124:127], v[148:151], v[164:167], v[124:127]
	v_mfma_i32_16x16x64_i8 v[120:123], v[144:147], v[168:171], v[120:123]
	v_mfma_i32_16x16x64_i8 v[120:123], v[148:151], v[192:195], v[120:123]
	v_mfma_i32_16x16x64_i8 v[116:119], v[144:147], v[196:199], v[116:119]
	v_mfma_i32_16x16x64_i8 v[116:119], v[148:151], v[200:203], v[116:119]
	v_mfma_i32_16x16x64_i8 v[112:115], v[144:147], v[204:207], v[112:115]
	v_mfma_i32_16x16x64_i8 v[112:115], v[148:151], v[208:211], v[112:115]
	v_mfma_i32_16x16x64_i8 v[60:63], v[152:155], v[204:207], v[60:63]
	v_mfma_i32_16x16x64_i8 v[60:63], v[156:159], v[208:211], v[60:63]
	v_mfma_i32_16x16x64_i8 v[80:83], v[152:155], v[196:199], v[80:83]
	v_mfma_i32_16x16x64_i8 v[80:83], v[156:159], v[200:203], v[80:83]
	s_setprio 2
	s_barrier
	v_mfma_i32_16x16x64_i8 v[72:75], v[152:155], v[168:171], v[72:75]
	v_mfma_i32_16x16x64_i8 v[72:75], v[156:159], v[192:195], v[72:75]
	v_mfma_i32_16x16x64_i8 v[68:71], v[152:155], v[160:163], v[68:71]
	v_mfma_i32_16x16x64_i8 v[68:71], v[156:159], v[164:167], v[68:71]
	s_setprio 0
	s_add_i32 s9, s9, s33
	s_mov_b32 m0, s9
	ds_read_b128 v[160:163], v189 offset:49152
	ds_read_b128 v[164:167], v189 offset:50176
	ds_read_b128 v[168:171], v189 offset:51200
	ds_read_b128 v[192:195], v189 offset:52224
	ds_read_b128 v[196:199], v189 offset:53248
	ds_read_b128 v[200:203], v189 offset:54272
	ds_read_b128 v[204:207], v189 offset:55296
	ds_read_b128 v[208:211], v189 offset:56320
	s_add_u32 s98, s100, s44
	s_addc_u32 s99, s101, s45
	global_load_lds_dwordx4 v174, s[98:99]
	s_add_i32 m0, s9, 0x2000
	s_add_i32 s9, s50, s33
	s_add_u32 s98, s100, s46
	s_addc_u32 s99, s101, s47
	global_load_lds_dwordx4 v174, s[98:99]
	s_mov_b32 m0, s9
	s_add_u32 s98, s100, s48
	s_addc_u32 s99, s101, s49
	global_load_lds_dwordx4 v174, s[98:99]
	s_add_i32 m0, s9, 0x2000
	s_nop 0
	s_add_u32 s98, s100, s52
	s_addc_u32 s99, s101, s53
	global_load_lds_dwordx4 v174, s[98:99]
	s_mov_b32 m0, s90
	s_nop 0
	s_add_u32 s98, vcc_lo, s44
	s_addc_u32 s99, vcc_hi, s45
	global_load_lds_dwordx4 v172, s[98:99]
	s_mov_b32 m0, s91
	s_nop 0
	s_add_u32 s98, vcc_lo, s46
	s_addc_u32 s99, vcc_hi, s47
	global_load_lds_dwordx4 v172, s[98:99]
	s_waitcnt vmcnt(8)
	s_waitcnt lgkmcnt(0)
	s_barrier
	s_setprio 1
	s_waitcnt lgkmcnt(0)
	v_mfma_i32_16x16x64_i8 v[48:51], v[128:131], v[160:163], v[48:51]
	v_mfma_i32_16x16x64_i8 v[48:51], v[132:135], v[164:167], v[48:51]
	v_mfma_i32_16x16x64_i8 v[52:55], v[128:131], v[168:171], v[52:55]
	v_mfma_i32_16x16x64_i8 v[52:55], v[132:135], v[192:195], v[52:55]
	v_mfma_i32_16x16x64_i8 v[56:59], v[128:131], v[196:199], v[56:59]
	v_mfma_i32_16x16x64_i8 v[56:59], v[132:135], v[200:203], v[56:59]
	v_mfma_i32_16x16x64_i8 v[64:67], v[128:131], v[204:207], v[64:67]
	v_mfma_i32_16x16x64_i8 v[64:67], v[132:135], v[208:211], v[64:67]
	v_mfma_i32_16x16x64_i8 v[12:15], v[136:139], v[204:207], v[12:15]
	v_mfma_i32_16x16x64_i8 v[12:15], v[140:143], v[208:211], v[12:15]
	v_mfma_i32_16x16x64_i8 v[8:11], v[136:139], v[196:199], v[8:11]
	v_mfma_i32_16x16x64_i8 v[8:11], v[140:143], v[200:203], v[8:11]
	v_mfma_i32_16x16x64_i8 v[4:7], v[136:139], v[168:171], v[4:7]
	v_mfma_i32_16x16x64_i8 v[4:7], v[140:143], v[192:195], v[4:7]
	v_mfma_i32_16x16x64_i8 v[0:3], v[136:139], v[160:163], v[0:3]
	v_mfma_i32_16x16x64_i8 v[0:3], v[140:143], v[164:167], v[0:3]
	s_setprio 0
	s_setprio 1
	v_mfma_i32_16x16x64_i8 v[108:111], v[144:147], v[160:163], v[108:111]
	v_mfma_i32_16x16x64_i8 v[108:111], v[148:151], v[164:167], v[108:111]
	v_mfma_i32_16x16x64_i8 v[104:107], v[144:147], v[168:171], v[104:107]
	v_mfma_i32_16x16x64_i8 v[104:107], v[148:151], v[192:195], v[104:107]
	v_mfma_i32_16x16x64_i8 v[100:103], v[144:147], v[196:199], v[100:103]
	v_mfma_i32_16x16x64_i8 v[100:103], v[148:151], v[200:203], v[100:103]
	v_mfma_i32_16x16x64_i8 v[76:79], v[144:147], v[204:207], v[76:79]
	v_mfma_i32_16x16x64_i8 v[76:79], v[148:151], v[208:211], v[76:79]
	v_mfma_i32_16x16x64_i8 v[36:39], v[152:155], v[204:207], v[36:39]
	v_mfma_i32_16x16x64_i8 v[36:39], v[156:159], v[208:211], v[36:39]
	v_mfma_i32_16x16x64_i8 v[32:35], v[152:155], v[196:199], v[32:35]
	v_mfma_i32_16x16x64_i8 v[32:35], v[156:159], v[200:203], v[32:35]
	s_setprio 2
	s_barrier
	v_mfma_i32_16x16x64_i8 v[40:43], v[152:155], v[168:171], v[40:43]
	v_mfma_i32_16x16x64_i8 v[40:43], v[156:159], v[192:195], v[40:43]
	v_mfma_i32_16x16x64_i8 v[44:47], v[152:155], v[160:163], v[44:47]
	v_mfma_i32_16x16x64_i8 v[44:47], v[156:159], v[164:167], v[44:47]
	s_setprio 0
	s_add_i32 s8, s8, 2
	s_add_u32 s75, s75, 0x100
	s_addc_u32 s78, s78, 0
	s_add_u32 s6, s6, 0x100
	s_addc_u32 s7, s7, 0
	s_cmp_gt_u32 s8, 29
	s_cbranch_scc0 .LBB0_800
	s_and_b64 vcc, exec, s[54:55]
	s_cbranch_vccz .LBB0_803
	s_barrier

.LBB0_1034:
	ds_read_b128 v[138:141], v151
	ds_read_b128 v[142:145], v151 offset:1024
	ds_read_b128 v[146:149], v151 offset:2048
	ds_read_b128 v[154:157], v151 offset:3072
	ds_read_b128 v[158:161], v152
	ds_read_b128 v[162:165], v152 offset:1024
	ds_read_b128 v[166:169], v152 offset:2048
	ds_read_b128 v[170:173], v152 offset:3072
	s_add_u32 s47, s44, 0xffd50080
	s_addc_u32 s64, s45, -1
	s_cmpk_eq_i32 s46, 0xa8
	s_cselect_b32 s65, s5, s64
	s_cselect_b32 s64, s4, s47
	s_cselect_b32 s67, s43, s63
	s_cselect_b32 s66, s42, s62
	s_add_i32 m0, s25, 0xc000
	ds_read_b128 v[174:177], v153
	ds_read_b128 v[178:181], v153 offset:1024
	ds_read_b128 v[182:185], v153 offset:2048
	ds_read_b128 v[186:189], v153 offset:3072
	ds_read_b128 v[190:193], v153 offset:4096
	ds_read_b128 v[194:197], v153 offset:5120
	ds_read_b128 v[198:201], v153 offset:6144
	ds_read_b128 v[202:205], v153 offset:7168
	global_load_lds_dwordx4 v132, s[44:45]
	s_add_i32 m0, s25, 0xe000
	s_nop 0
	s_add_u32 s98, s44, s0
	s_addc_u32 s99, s45, s1
	global_load_lds_dwordx4 v132, s[98:99]
	s_waitcnt vmcnt(8)
	s_waitcnt lgkmcnt(0)
	s_barrier
	s_setprio 1
	s_waitcnt lgkmcnt(0)
	v_mfma_f32_16x16x32_bf16 v[124:127], v[138:141], v[174:177], v[124:127]
	v_mfma_f32_16x16x32_bf16 v[124:127], v[142:145], v[178:181], v[124:127]
	v_mfma_f32_16x16x32_bf16 v[116:119], v[138:141], v[182:185], v[116:119]
	v_mfma_f32_16x16x32_bf16 v[116:119], v[142:145], v[186:189], v[116:119]
	v_mfma_f32_16x16x32_bf16 v[108:111], v[138:141], v[190:193], v[108:111]
	v_mfma_f32_16x16x32_bf16 v[108:111], v[142:145], v[194:197], v[108:111]
	v_mfma_f32_16x16x32_bf16 v[100:103], v[138:141], v[198:201], v[100:103]
	v_mfma_f32_16x16x32_bf16 v[100:103], v[142:145], v[202:205], v[100:103]
	v_mfma_f32_16x16x32_bf16 v[96:99], v[146:149], v[198:201], v[96:99]
	v_mfma_f32_16x16x32_bf16 v[96:99], v[154:157], v[202:205], v[96:99]
	v_mfma_f32_16x16x32_bf16 v[104:107], v[146:149], v[190:193], v[104:107]
	v_mfma_f32_16x16x32_bf16 v[104:107], v[154:157], v[194:197], v[104:107]
	v_mfma_f32_16x16x32_bf16 v[112:115], v[146:149], v[182:185], v[112:115]
	v_mfma_f32_16x16x32_bf16 v[112:115], v[154:157], v[186:189], v[112:115]
	v_mfma_f32_16x16x32_bf16 v[120:123], v[146:149], v[174:177], v[120:123]
	v_mfma_f32_16x16x32_bf16 v[120:123], v[154:157], v[178:181], v[120:123]
	s_setprio 0
	s_setprio 1
	v_mfma_f32_16x16x32_bf16 v[92:95], v[158:161], v[174:177], v[92:95]
	v_mfma_f32_16x16x32_bf16 v[92:95], v[162:165], v[178:181], v[92:95]
	v_mfma_f32_16x16x32_bf16 v[84:87], v[158:161], v[182:185], v[84:87]
	v_mfma_f32_16x16x32_bf16 v[84:87], v[162:165], v[186:189], v[84:87]
	v_mfma_f32_16x16x32_bf16 v[76:79], v[158:161], v[190:193], v[76:79]
	v_mfma_f32_16x16x32_bf16 v[76:79], v[162:165], v[194:197], v[76:79]
	v_mfma_f32_16x16x32_bf16 v[68:71], v[158:161], v[198:201], v[68:71]
	v_mfma_f32_16x16x32_bf16 v[68:71], v[162:165], v[202:205], v[68:71]
	v_mfma_f32_16x16x32_bf16 v[64:67], v[166:169], v[198:201], v[64:67]
	v_mfma_f32_16x16x32_bf16 v[64:67], v[170:173], v[202:205], v[64:67]
	v_mfma_f32_16x16x32_bf16 v[72:75], v[166:169], v[190:193], v[72:75]
	v_mfma_f32_16x16x32_bf16 v[72:75], v[170:173], v[194:197], v[72:75]
	s_setprio 2
	s_barrier
	v_mfma_f32_16x16x32_bf16 v[80:83], v[166:169], v[182:185], v[80:83]
	v_mfma_f32_16x16x32_bf16 v[80:83], v[170:173], v[186:189], v[80:83]
	v_mfma_f32_16x16x32_bf16 v[88:91], v[166:169], v[174:177], v[88:91]
	v_mfma_f32_16x16x32_bf16 v[88:91], v[170:173], v[178:181], v[88:91]
	s_setprio 0
	s_add_i32 s47, s56, s24
	s_mov_b32 m0, s47
	ds_read_b128 v[174:177], v153 offset:16384
	ds_read_b128 v[178:181], v153 offset:17408
	ds_read_b128 v[182:185], v153 offset:18432
	ds_read_b128 v[186:189], v153 offset:19456
	ds_read_b128 v[190:193], v153 offset:20480
	ds_read_b128 v[194:197], v153 offset:21504
	ds_read_b128 v[198:201], v153 offset:22528
	ds_read_b128 v[202:205], v153 offset:23552
	global_load_lds_dwordx4 v130, s[66:67]
	s_add_i32 m0, s47, 0x2000
	s_add_i32 s47, s57, s24
	s_add_u32 s98, s66, s0
	s_addc_u32 s99, s67, s1
	global_load_lds_dwordx4 v130, s[98:99]
	s_mov_b32 m0, s47
	s_nop 0
	s_add_u32 s98, s66, s6
	s_addc_u32 s99, s67, s7
	global_load_lds_dwordx4 v130, s[98:99]
	s_add_i32 m0, s47, 0x2000
	s_nop 0
	s_add_u32 s98, s66, s8
	s_addc_u32 s99, s67, s9
	global_load_lds_dwordx4 v130, s[98:99]
	s_mov_b64 s[100:101], s[64:65]
	s_mov_b32 m0, s25
	s_nop 0
	global_load_lds_dwordx4 v128, s[64:65]
	s_mov_b32 m0, s33
	s_nop 0
	s_add_u32 s98, s64, s0
	s_addc_u32 s99, s65, s1
	global_load_lds_dwordx4 v128, s[98:99]
	s_waitcnt vmcnt(8)
	s_waitcnt lgkmcnt(0)
	s_barrier
	s_setprio 1
	s_waitcnt lgkmcnt(0)
	v_mfma_f32_16x16x32_bf16 v[60:63], v[138:141], v[174:177], v[60:63]
	v_mfma_f32_16x16x32_bf16 v[60:63], v[142:145], v[178:181], v[60:63]
	v_mfma_f32_16x16x32_bf16 v[52:55], v[138:141], v[182:185], v[52:55]
	v_mfma_f32_16x16x32_bf16 v[52:55], v[142:145], v[186:189], v[52:55]
	v_mfma_f32_16x16x32_bf16 v[44:47], v[138:141], v[190:193], v[44:47]
	v_mfma_f32_16x16x32_bf16 v[44:47], v[142:145], v[194:197], v[44:47]
	v_mfma_f32_16x16x32_bf16 v[36:39], v[138:141], v[198:201], v[36:39]
	v_mfma_f32_16x16x32_bf16 v[36:39], v[142:145], v[202:205], v[36:39]
	v_mfma_f32_16x16x32_bf16 v[32:35], v[146:149], v[198:201], v[32:35]
	v_mfma_f32_16x16x32_bf16 v[32:35], v[154:157], v[202:205], v[32:35]
	v_mfma_f32_16x16x32_bf16 v[40:43], v[146:149], v[190:193], v[40:43]
	v_mfma_f32_16x16x32_bf16 v[40:43], v[154:157], v[194:197], v[40:43]
	v_mfma_f32_16x16x32_bf16 v[48:51], v[146:149], v[182:185], v[48:51]
	v_mfma_f32_16x16x32_bf16 v[48:51], v[154:157], v[186:189], v[48:51]
	v_mfma_f32_16x16x32_bf16 v[56:59], v[146:149], v[174:177], v[56:59]
	v_mfma_f32_16x16x32_bf16 v[56:59], v[154:157], v[178:181], v[56:59]
	s_setprio 0
	s_setprio 1
	v_mfma_f32_16x16x32_bf16 v[28:31], v[158:161], v[174:177], v[28:31]
	v_mfma_f32_16x16x32_bf16 v[28:31], v[162:165], v[178:181], v[28:31]
	v_mfma_f32_16x16x32_bf16 v[20:23], v[158:161], v[182:185], v[20:23]
	v_mfma_f32_16x16x32_bf16 v[20:23], v[162:165], v[186:189], v[20:23]
	v_mfma_f32_16x16x32_bf16 v[12:15], v[158:161], v[190:193], v[12:15]
	v_mfma_f32_16x16x32_bf16 v[12:15], v[162:165], v[194:197], v[12:15]
	v_mfma_f32_16x16x32_bf16 v[4:7], v[158:161], v[198:201], v[4:7]
	v_mfma_f32_16x16x32_bf16 v[4:7], v[162:165], v[202:205], v[4:7]
	v_mfma_f32_16x16x32_bf16 v[0:3], v[166:169], v[198:201], v[0:3]
	v_mfma_f32_16x16x32_bf16 v[0:3], v[170:173], v[202:205], v[0:3]
	v_mfma_f32_16x16x32_bf16 v[8:11], v[166:169], v[190:193], v[8:11]
	v_mfma_f32_16x16x32_bf16 v[8:11], v[170:173], v[194:197], v[8:11]
	s_setprio 2
	s_barrier
	v_mfma_f32_16x16x32_bf16 v[16:19], v[166:169], v[182:185], v[16:19]
	v_mfma_f32_16x16x32_bf16 v[16:19], v[170:173], v[186:189], v[16:19]
	v_mfma_f32_16x16x32_bf16 v[24:27], v[166:169], v[174:177], v[24:27]
	v_mfma_f32_16x16x32_bf16 v[24:27], v[170:173], v[178:181], v[24:27]
	s_setprio 0
	s_add_i32 s47, 0, 0x18000
	s_add_i32 s64, 0, 0x1c000
	v_add_u32_e32 v154, s47, v150
	v_add_u32_e32 v170, s64, v150
	ds_read_b128 v[138:141], v154
	ds_read_b128 v[142:145], v154 offset:1024
	ds_read_b128 v[146:149], v154 offset:2048
	ds_read_b128 v[154:157], v154 offset:3072
	ds_read_b128 v[158:161], v170
	ds_read_b128 v[162:165], v170 offset:1024
	ds_read_b128 v[166:169], v170 offset:2048
	ds_read_b128 v[170:173], v170 offset:3072
	s_mov_b32 m0, s48
	ds_read_b128 v[174:177], v153 offset:32768
	ds_read_b128 v[178:181], v153 offset:33792
	ds_read_b128 v[182:185], v153 offset:34816
	ds_read_b128 v[186:189], v153 offset:35840
	ds_read_b128 v[190:193], v153 offset:36864
	ds_read_b128 v[194:197], v153 offset:37888
	ds_read_b128 v[198:201], v153 offset:38912
	ds_read_b128 v[202:205], v153 offset:39936
	s_add_u32 s98, s100, s6
	s_addc_u32 s99, s101, s7
	global_load_lds_dwordx4 v128, s[98:99]
	s_mov_b32 m0, s49
	s_nop 0
	s_add_u32 s98, s100, s8
	s_addc_u32 s99, s101, s9
	global_load_lds_dwordx4 v128, s[98:99]
	s_waitcnt vmcnt(8)
	s_waitcnt lgkmcnt(0)
	s_barrier
	s_setprio 1
	s_waitcnt lgkmcnt(0)
	v_mfma_f32_16x16x32_bf16 v[124:127], v[138:141], v[174:177], v[124:127]
	v_mfma_f32_16x16x32_bf16 v[124:127], v[142:145], v[178:181], v[124:127]
	v_mfma_f32_16x16x32_bf16 v[116:119], v[138:141], v[182:185], v[116:119]
	v_mfma_f32_16x16x32_bf16 v[116:119], v[142:145], v[186:189], v[116:119]
	v_mfma_f32_16x16x32_bf16 v[108:111], v[138:141], v[190:193], v[108:111]
	v_mfma_f32_16x16x32_bf16 v[108:111], v[142:145], v[194:197], v[108:111]
	v_mfma_f32_16x16x32_bf16 v[100:103], v[138:141], v[198:201], v[100:103]
	v_mfma_f32_16x16x32_bf16 v[100:103], v[142:145], v[202:205], v[100:103]
	v_mfma_f32_16x16x32_bf16 v[96:99], v[146:149], v[198:201], v[96:99]
	v_mfma_f32_16x16x32_bf16 v[96:99], v[154:157], v[202:205], v[96:99]
	v_mfma_f32_16x16x32_bf16 v[104:107], v[146:149], v[190:193], v[104:107]
	v_mfma_f32_16x16x32_bf16 v[104:107], v[154:157], v[194:197], v[104:107]
	v_mfma_f32_16x16x32_bf16 v[112:115], v[146:149], v[182:185], v[112:115]
	v_mfma_f32_16x16x32_bf16 v[112:115], v[154:157], v[186:189], v[112:115]
	v_mfma_f32_16x16x32_bf16 v[120:123], v[146:149], v[174:177], v[120:123]
	v_mfma_f32_16x16x32_bf16 v[120:123], v[154:157], v[178:181], v[120:123]
	s_setprio 0
	s_setprio 1
	v_mfma_f32_16x16x32_bf16 v[92:95], v[158:161], v[174:177], v[92:95]
	v_mfma_f32_16x16x32_bf16 v[92:95], v[162:165], v[178:181], v[92:95]
	v_mfma_f32_16x16x32_bf16 v[84:87], v[158:161], v[182:185], v[84:87]
	v_mfma_f32_16x16x32_bf16 v[84:87], v[162:165], v[186:189], v[84:87]
	v_mfma_f32_16x16x32_bf16 v[76:79], v[158:161], v[190:193], v[76:79]
	v_mfma_f32_16x16x32_bf16 v[76:79], v[162:165], v[194:197], v[76:79]
	v_mfma_f32_16x16x32_bf16 v[68:71], v[158:161], v[198:201], v[68:71]
	v_mfma_f32_16x16x32_bf16 v[68:71], v[162:165], v[202:205], v[68:71]
	v_mfma_f32_16x16x32_bf16 v[64:67], v[166:169], v[198:201], v[64:67]
	v_mfma_f32_16x16x32_bf16 v[64:67], v[170:173], v[202:205], v[64:67]
	v_mfma_f32_16x16x32_bf16 v[72:75], v[166:169], v[190:193], v[72:75]
	v_mfma_f32_16x16x32_bf16 v[72:75], v[170:173], v[194:197], v[72:75]
	s_setprio 2
	s_barrier
	v_mfma_f32_16x16x32_bf16 v[80:83], v[166:169], v[182:185], v[80:83]
	v_mfma_f32_16x16x32_bf16 v[80:83], v[170:173], v[186:189], v[80:83]
	v_mfma_f32_16x16x32_bf16 v[88:91], v[166:169], v[174:177], v[88:91]
	v_mfma_f32_16x16x32_bf16 v[88:91], v[170:173], v[178:181], v[88:91]
	s_setprio 0
	s_add_i32 s47, s47, s24
	s_mov_b32 m0, s47
	ds_read_b128 v[174:177], v153 offset:49152
	ds_read_b128 v[178:181], v153 offset:50176
	ds_read_b128 v[182:185], v153 offset:51200
	ds_read_b128 v[186:189], v153 offset:52224
	ds_read_b128 v[190:193], v153 offset:53248
	ds_read_b128 v[194:197], v153 offset:54272
	ds_read_b128 v[198:201], v153 offset:55296
	ds_read_b128 v[202:205], v153 offset:56320
	s_add_u32 s98, s66, s16
	s_addc_u32 s99, s67, s17
	global_load_lds_dwordx4 v130, s[98:99]
	s_add_i32 m0, s47, 0x2000
	s_add_i32 s47, s64, s24
	s_add_u32 s98, s66, s20
	s_addc_u32 s99, s67, s21
	global_load_lds_dwordx4 v130, s[98:99]
	s_mov_b32 m0, s47
	s_add_u32 s98, s66, s34
	s_addc_u32 s99, s67, s35
	global_load_lds_dwordx4 v130, s[98:99]
	s_add_i32 m0, s47, 0x2000
	s_nop 0
	s_add_u32 s98, s66, s36
	s_addc_u32 s99, s67, s37
	global_load_lds_dwordx4 v130, s[98:99]
	s_mov_b32 m0, s51
	s_nop 0
	s_add_u32 s98, s100, s16
	s_addc_u32 s99, s101, s17
	global_load_lds_dwordx4 v128, s[98:99]
	s_mov_b32 m0, s52
	s_nop 0
	s_add_u32 s98, s100, s20
	s_addc_u32 s99, s101, s21
	global_load_lds_dwordx4 v128, s[98:99]
	s_waitcnt vmcnt(8)
	s_waitcnt lgkmcnt(0)
	s_barrier
	s_setprio 1
	s_waitcnt lgkmcnt(0)
	v_mfma_f32_16x16x32_bf16 v[60:63], v[138:141], v[174:177], v[60:63]
	v_mfma_f32_16x16x32_bf16 v[60:63], v[142:145], v[178:181], v[60:63]
	v_mfma_f32_16x16x32_bf16 v[52:55], v[138:141], v[182:185], v[52:55]
	v_mfma_f32_16x16x32_bf16 v[52:55], v[142:145], v[186:189], v[52:55]
	v_mfma_f32_16x16x32_bf16 v[44:47], v[138:141], v[190:193], v[44:47]
	v_mfma_f32_16x16x32_bf16 v[44:47], v[142:145], v[194:197], v[44:47]
	v_mfma_f32_16x16x32_bf16 v[36:39], v[138:141], v[198:201], v[36:39]
	v_mfma_f32_16x16x32_bf16 v[36:39], v[142:145], v[202:205], v[36:39]
	v_mfma_f32_16x16x32_bf16 v[32:35], v[146:149], v[198:201], v[32:35]
	v_mfma_f32_16x16x32_bf16 v[32:35], v[154:157], v[202:205], v[32:35]
	v_mfma_f32_16x16x32_bf16 v[40:43], v[146:149], v[190:193], v[40:43]
	v_mfma_f32_16x16x32_bf16 v[40:43], v[154:157], v[194:197], v[40:43]
	v_mfma_f32_16x16x32_bf16 v[48:51], v[146:149], v[182:185], v[48:51]
	v_mfma_f32_16x16x32_bf16 v[48:51], v[154:157], v[186:189], v[48:51]
	v_mfma_f32_16x16x32_bf16 v[56:59], v[146:149], v[174:177], v[56:59]
	v_mfma_f32_16x16x32_bf16 v[56:59], v[154:157], v[178:181], v[56:59]
	s_setprio 0
	s_setprio 1
	v_mfma_f32_16x16x32_bf16 v[28:31], v[158:161], v[174:177], v[28:31]
	v_mfma_f32_16x16x32_bf16 v[28:31], v[162:165], v[178:181], v[28:31]
	v_mfma_f32_16x16x32_bf16 v[20:23], v[158:161], v[182:185], v[20:23]
	v_mfma_f32_16x16x32_bf16 v[20:23], v[162:165], v[186:189], v[20:23]
	v_mfma_f32_16x16x32_bf16 v[12:15], v[158:161], v[190:193], v[12:15]
	v_mfma_f32_16x16x32_bf16 v[12:15], v[162:165], v[194:197], v[12:15]
	v_mfma_f32_16x16x32_bf16 v[4:7], v[158:161], v[198:201], v[4:7]
	v_mfma_f32_16x16x32_bf16 v[4:7], v[162:165], v[202:205], v[4:7]
	v_mfma_f32_16x16x32_bf16 v[0:3], v[166:169], v[198:201], v[0:3]
	v_mfma_f32_16x16x32_bf16 v[0:3], v[170:173], v[202:205], v[0:3]
	v_mfma_f32_16x16x32_bf16 v[8:11], v[166:169], v[190:193], v[8:11]
	v_mfma_f32_16x16x32_bf16 v[8:11], v[170:173], v[194:197], v[8:11]
	s_setprio 2
	s_barrier
	v_mfma_f32_16x16x32_bf16 v[16:19], v[166:169], v[182:185], v[16:19]
	v_mfma_f32_16x16x32_bf16 v[16:19], v[170:173], v[186:189], v[16:19]
	v_mfma_f32_16x16x32_bf16 v[24:27], v[166:169], v[174:177], v[24:27]
	v_mfma_f32_16x16x32_bf16 v[24:27], v[170:173], v[178:181], v[24:27]
	s_setprio 0
	s_add_i32 s46, s46, 2
	s_add_u32 s62, s62, 0x100
	s_addc_u32 s63, s63, 0
	s_add_u32 s44, s44, 0x100
	s_addc_u32 s45, s45, 0
	s_cmpk_gt_u32 s46, 0xa9
	s_cbranch_scc0 .LBB0_1034
	s_and_b64 vcc, exec, s[38:39]
	s_cbranch_vccz .LBB0_1037
	s_barrier

.LBB0_1180:
	ds_read_b128 v[112:115], v181
	ds_read_b128 v[116:119], v181 offset:1024
	ds_read_b128 v[128:131], v181 offset:2048
	ds_read_b128 v[142:145], v181 offset:3072
	ds_read_b128 v[146:149], v202
	ds_read_b128 v[150:153], v202 offset:1024
	ds_read_b128 v[154:157], v202 offset:2048
	ds_read_b128 v[168:171], v202 offset:3072
	s_add_u32 s49, s46, 0xfff80080
	s_addc_u32 s70, s47, -1
	s_cmp_eq_u32 s48, 28
	s_cselect_b32 s71, s39, s70
	s_cselect_b32 s70, s66, s49
	s_cselect_b32 s73, s37, s69
	s_cselect_b32 s72, s67, s68
	s_add_i32 m0, s45, 0xc000
	ds_read_b128 v[172:175], v203
	ds_read_b128 v[182:185], v203 offset:1024
	ds_read_b128 v[186:189], v203 offset:2048
	ds_read_b128 v[190:193], v203 offset:3072
	ds_read_b128 v[194:197], v203 offset:4096
	ds_read_b128 v[198:201], v203 offset:5120
	ds_read_b128 v[206:209], v203 offset:6144
	ds_read_b128 v[210:213], v203 offset:7168
	global_load_lds_dwordx4 v162, s[46:47]
	s_add_i32 m0, s45, 0xe000
	s_nop 0
	s_add_u32 s98, s46, s2
	s_addc_u32 s99, s47, s3
	global_load_lds_dwordx4 v162, s[98:99]
	s_waitcnt vmcnt(8)
	s_waitcnt lgkmcnt(0)
	s_barrier
	s_setprio 1
	s_waitcnt lgkmcnt(0)
	v_mfma_i32_16x16x64_i8 v[138:141], v[112:115], v[172:175], v[138:141]
	v_mfma_i32_16x16x64_i8 v[132:135], v[128:131], v[172:175], v[134:137]
	v_mfma_i32_16x16x64_i8 v[124:127], v[112:115], v[186:189], v[124:127]
	v_mfma_i32_16x16x64_i8 v[120:123], v[128:131], v[186:189], v[120:123]
	v_mfma_i32_16x16x64_i8 v[108:111], v[112:115], v[194:197], v[108:111]
	v_mfma_i32_16x16x64_i8 v[104:107], v[128:131], v[194:197], v[104:107]
	v_mfma_i32_16x16x64_i8 v[100:103], v[112:115], v[206:209], v[100:103]
	v_mfma_i32_16x16x64_i8 v[96:99], v[128:131], v[206:209], v[96:99]
	v_mfma_i32_16x16x64_i8 v[138:141], v[116:119], v[182:185], v[138:141]
	v_mfma_i32_16x16x64_i8 v[132:135], v[142:145], v[182:185], v[132:135]
	v_mfma_i32_16x16x64_i8 v[124:127], v[116:119], v[190:193], v[124:127]
	v_mfma_i32_16x16x64_i8 v[120:123], v[142:145], v[190:193], v[120:123]
	v_mfma_i32_16x16x64_i8 v[108:111], v[116:119], v[198:201], v[108:111]
	v_mfma_i32_16x16x64_i8 v[104:107], v[142:145], v[198:201], v[104:107]
	v_mfma_i32_16x16x64_i8 v[100:103], v[116:119], v[210:213], v[100:103]
	v_mfma_i32_16x16x64_i8 v[96:99], v[142:145], v[210:213], v[96:99]
	s_setprio 0
	s_setprio 1
	v_mfma_i32_16x16x64_i8 v[60:63], v[146:149], v[172:175], v[60:63]
	v_mfma_i32_16x16x64_i8 v[60:63], v[150:153], v[182:185], v[60:63]
	v_mfma_i32_16x16x64_i8 v[56:59], v[154:157], v[172:175], v[56:59]
	v_mfma_i32_16x16x64_i8 v[56:59], v[168:171], v[182:185], v[56:59]
	v_mfma_i32_16x16x64_i8 v[52:55], v[146:149], v[186:189], v[52:55]
	v_mfma_i32_16x16x64_i8 v[52:55], v[150:153], v[190:193], v[52:55]
	v_mfma_i32_16x16x64_i8 v[48:51], v[154:157], v[186:189], v[48:51]
	v_mfma_i32_16x16x64_i8 v[48:51], v[168:171], v[190:193], v[48:51]
	v_mfma_i32_16x16x64_i8 v[44:47], v[146:149], v[194:197], v[44:47]
	v_mfma_i32_16x16x64_i8 v[44:47], v[150:153], v[198:201], v[44:47]
	v_mfma_i32_16x16x64_i8 v[40:43], v[154:157], v[194:197], v[40:43]
	v_mfma_i32_16x16x64_i8 v[40:43], v[168:171], v[198:201], v[40:43]
	s_setprio 2
	s_barrier
	v_mfma_i32_16x16x64_i8 v[36:39], v[146:149], v[206:209], v[36:39]
	v_mfma_i32_16x16x64_i8 v[36:39], v[150:153], v[210:213], v[36:39]
	v_mfma_i32_16x16x64_i8 v[32:35], v[154:157], v[206:209], v[32:35]
	v_mfma_i32_16x16x64_i8 v[32:35], v[168:171], v[210:213], v[32:35]
	s_setprio 0
	s_add_i32 s49, s61, s33
	s_mov_b32 m0, s49
	ds_read_b128 v[172:175], v203 offset:16384
	ds_read_b128 v[182:185], v203 offset:17408
	ds_read_b128 v[186:189], v203 offset:18432
	ds_read_b128 v[190:193], v203 offset:19456
	ds_read_b128 v[194:197], v203 offset:20480
	ds_read_b128 v[198:201], v203 offset:21504
	ds_read_b128 v[206:209], v203 offset:22528
	ds_read_b128 v[210:213], v203 offset:23552
	global_load_lds_dwordx4 v160, s[72:73]
	s_add_i32 m0, s49, 0x2000
	s_add_i32 s49, s62, s33
	s_add_u32 s98, s72, s2
	s_addc_u32 s99, s73, s3
	global_load_lds_dwordx4 v160, s[98:99]
	s_mov_b32 m0, s49
	s_mov_b64 s[100:101], s[70:71]
	s_add_u32 s98, s72, s6
	s_addc_u32 s99, s73, s7
	global_load_lds_dwordx4 v160, s[98:99]
	s_add_i32 m0, s49, 0x2000
	s_nop 0
	s_add_u32 s98, s72, s8
	s_addc_u32 s99, s73, s9
	global_load_lds_dwordx4 v160, s[98:99]
	s_mov_b32 m0, s45
	s_nop 0
	global_load_lds_dwordx4 v158, s[70:71]
	s_mov_b32 m0, s50
	s_nop 0
	s_add_u32 s98, s70, s2
	s_addc_u32 s99, s71, s3
	global_load_lds_dwordx4 v158, s[98:99]
	s_waitcnt vmcnt(8)
	s_waitcnt lgkmcnt(0)
	s_barrier
	s_setprio 1
	s_waitcnt lgkmcnt(0)
	v_mfma_i32_16x16x64_i8 v[92:95], v[112:115], v[172:175], v[92:95]
	v_mfma_i32_16x16x64_i8 v[92:95], v[116:119], v[182:185], v[92:95]
	v_mfma_i32_16x16x64_i8 v[84:87], v[112:115], v[186:189], v[84:87]
	v_mfma_i32_16x16x64_i8 v[84:87], v[116:119], v[190:193], v[84:87]
	v_mfma_i32_16x16x64_i8 v[76:79], v[112:115], v[194:197], v[76:79]
	v_mfma_i32_16x16x64_i8 v[76:79], v[116:119], v[198:201], v[76:79]
	v_mfma_i32_16x16x64_i8 v[68:71], v[112:115], v[206:209], v[68:71]
	v_mfma_i32_16x16x64_i8 v[68:71], v[116:119], v[210:213], v[68:71]
	v_mfma_i32_16x16x64_i8 v[64:67], v[128:131], v[206:209], v[64:67]
	v_mfma_i32_16x16x64_i8 v[64:67], v[142:145], v[210:213], v[64:67]
	v_mfma_i32_16x16x64_i8 v[72:75], v[128:131], v[194:197], v[72:75]
	v_mfma_i32_16x16x64_i8 v[72:75], v[142:145], v[198:201], v[72:75]
	v_mfma_i32_16x16x64_i8 v[80:83], v[128:131], v[186:189], v[80:83]
	v_mfma_i32_16x16x64_i8 v[80:83], v[142:145], v[190:193], v[80:83]
	v_mfma_i32_16x16x64_i8 v[88:91], v[128:131], v[172:175], v[88:91]
	v_mfma_i32_16x16x64_i8 v[88:91], v[142:145], v[182:185], v[88:91]
	s_setprio 0
	s_setprio 1
	v_mfma_i32_16x16x64_i8 v[28:31], v[146:149], v[172:175], v[28:31]
	v_mfma_i32_16x16x64_i8 v[28:31], v[150:153], v[182:185], v[28:31]
	v_mfma_i32_16x16x64_i8 v[20:23], v[146:149], v[186:189], v[20:23]
	v_mfma_i32_16x16x64_i8 v[20:23], v[150:153], v[190:193], v[20:23]
	v_mfma_i32_16x16x64_i8 v[12:15], v[146:149], v[194:197], v[12:15]
	v_mfma_i32_16x16x64_i8 v[12:15], v[150:153], v[198:201], v[12:15]
	v_mfma_i32_16x16x64_i8 v[4:7], v[146:149], v[206:209], v[4:7]
	v_mfma_i32_16x16x64_i8 v[4:7], v[150:153], v[210:213], v[4:7]
	v_mfma_i32_16x16x64_i8 v[0:3], v[154:157], v[206:209], v[0:3]
	v_mfma_i32_16x16x64_i8 v[0:3], v[168:171], v[210:213], v[0:3]
	v_mfma_i32_16x16x64_i8 v[8:11], v[154:157], v[194:197], v[8:11]
	v_mfma_i32_16x16x64_i8 v[8:11], v[168:171], v[198:201], v[8:11]
	s_setprio 2
	s_barrier
	v_mfma_i32_16x16x64_i8 v[16:19], v[154:157], v[186:189], v[16:19]
	v_mfma_i32_16x16x64_i8 v[16:19], v[168:171], v[190:193], v[16:19]
	v_mfma_i32_16x16x64_i8 v[24:27], v[154:157], v[172:175], v[24:27]
	v_mfma_i32_16x16x64_i8 v[24:27], v[168:171], v[182:185], v[24:27]
	s_setprio 0
	s_add_i32 s49, 0, 0x18000
	v_add_u32_e32 v136, s49, v179
	s_add_i32 s70, 0, 0x1c000
	ds_read_b128 v[112:115], v136
	ds_read_b128 v[116:119], v136 offset:1024
	ds_read_b128 v[128:131], v136 offset:2048
	ds_read_b128 v[142:145], v136 offset:3072
	v_add_u32_e32 v136, s70, v179
	ds_read_b128 v[146:149], v136
	ds_read_b128 v[150:153], v136 offset:1024
	ds_read_b128 v[154:157], v136 offset:2048
	ds_read_b128 v[168:171], v136 offset:3072
	s_mov_b32 m0, s51
	ds_read_b128 v[172:175], v203 offset:32768
	ds_read_b128 v[182:185], v203 offset:33792
	ds_read_b128 v[186:189], v203 offset:34816
	ds_read_b128 v[190:193], v203 offset:35840
	ds_read_b128 v[194:197], v203 offset:36864
	ds_read_b128 v[198:201], v203 offset:37888
	ds_read_b128 v[206:209], v203 offset:38912
	ds_read_b128 v[210:213], v203 offset:39936
	s_add_u32 s98, s100, s6
	s_addc_u32 s99, s101, s7
	global_load_lds_dwordx4 v158, s[98:99]
	s_mov_b32 m0, s52
	s_nop 0
	s_add_u32 s98, s100, s8
	s_addc_u32 s99, s101, s9
	global_load_lds_dwordx4 v158, s[98:99]
	s_waitcnt vmcnt(8)
	s_waitcnt lgkmcnt(0)
	s_barrier
	s_setprio 1
	s_waitcnt lgkmcnt(0)
	v_mfma_i32_16x16x64_i8 v[136:139], v[112:115], v[172:175], v[138:141]
	v_mfma_i32_16x16x64_i8 v[132:135], v[128:131], v[172:175], v[132:135]
	v_mfma_i32_16x16x64_i8 v[124:127], v[112:115], v[186:189], v[124:127]
	v_mfma_i32_16x16x64_i8 v[120:123], v[128:131], v[186:189], v[120:123]
	v_mfma_i32_16x16x64_i8 v[108:111], v[112:115], v[194:197], v[108:111]
	v_mfma_i32_16x16x64_i8 v[104:107], v[128:131], v[194:197], v[104:107]
	v_mfma_i32_16x16x64_i8 v[100:103], v[112:115], v[206:209], v[100:103]
	v_mfma_i32_16x16x64_i8 v[96:99], v[128:131], v[206:209], v[96:99]
	v_mfma_i32_16x16x64_i8 v[138:141], v[116:119], v[182:185], v[136:139]
	v_mfma_i32_16x16x64_i8 v[134:137], v[142:145], v[182:185], v[132:135]
	v_mfma_i32_16x16x64_i8 v[124:127], v[116:119], v[190:193], v[124:127]
	v_mfma_i32_16x16x64_i8 v[120:123], v[142:145], v[190:193], v[120:123]
	v_mfma_i32_16x16x64_i8 v[108:111], v[116:119], v[198:201], v[108:111]
	v_mfma_i32_16x16x64_i8 v[104:107], v[142:145], v[198:201], v[104:107]
	v_mfma_i32_16x16x64_i8 v[100:103], v[116:119], v[210:213], v[100:103]
	v_mfma_i32_16x16x64_i8 v[96:99], v[142:145], v[210:213], v[96:99]
	s_setprio 0
	s_setprio 1
	v_mfma_i32_16x16x64_i8 v[60:63], v[146:149], v[172:175], v[60:63]
	v_mfma_i32_16x16x64_i8 v[60:63], v[150:153], v[182:185], v[60:63]
	v_mfma_i32_16x16x64_i8 v[56:59], v[154:157], v[172:175], v[56:59]
	v_mfma_i32_16x16x64_i8 v[56:59], v[168:171], v[182:185], v[56:59]
	v_mfma_i32_16x16x64_i8 v[52:55], v[146:149], v[186:189], v[52:55]
	v_mfma_i32_16x16x64_i8 v[52:55], v[150:153], v[190:193], v[52:55]
	v_mfma_i32_16x16x64_i8 v[48:51], v[154:157], v[186:189], v[48:51]
	v_mfma_i32_16x16x64_i8 v[48:51], v[168:171], v[190:193], v[48:51]
	v_mfma_i32_16x16x64_i8 v[44:47], v[146:149], v[194:197], v[44:47]
	v_mfma_i32_16x16x64_i8 v[44:47], v[150:153], v[198:201], v[44:47]
	v_mfma_i32_16x16x64_i8 v[40:43], v[154:157], v[194:197], v[40:43]
	v_mfma_i32_16x16x64_i8 v[40:43], v[168:171], v[198:201], v[40:43]
	s_setprio 2
	s_barrier
	v_mfma_i32_16x16x64_i8 v[36:39], v[146:149], v[206:209], v[36:39]
	v_mfma_i32_16x16x64_i8 v[36:39], v[150:153], v[210:213], v[36:39]
	v_mfma_i32_16x16x64_i8 v[32:35], v[154:157], v[206:209], v[32:35]
	v_mfma_i32_16x16x64_i8 v[32:35], v[168:171], v[210:213], v[32:35]
	s_setprio 0
	s_add_i32 s49, s49, s33
	s_mov_b32 m0, s49
	ds_read_b128 v[172:175], v203 offset:49152
	ds_read_b128 v[182:185], v203 offset:50176
	ds_read_b128 v[186:189], v203 offset:51200
	ds_read_b128 v[190:193], v203 offset:52224
	ds_read_b128 v[194:197], v203 offset:53248
	ds_read_b128 v[198:201], v203 offset:54272
	ds_read_b128 v[206:209], v203 offset:55296
	ds_read_b128 v[210:213], v203 offset:56320
	s_add_u32 s98, s72, s16
	s_addc_u32 s99, s73, s17
	global_load_lds_dwordx4 v160, s[98:99]
	s_add_i32 m0, s49, 0x2000
	s_add_i32 s49, s70, s33
	s_add_u32 s98, s72, s18
	s_addc_u32 s99, s73, s19
	global_load_lds_dwordx4 v160, s[98:99]
	s_mov_b32 m0, s49
	s_nop 0
	s_add_u32 s98, s72, s20
	s_addc_u32 s99, s73, s21
	global_load_lds_dwordx4 v160, s[98:99]
	s_add_i32 m0, s49, 0x2000
	s_nop 0
	s_add_u32 s98, s72, s30
	s_addc_u32 s99, s73, s31
	global_load_lds_dwordx4 v160, s[98:99]
	s_mov_b32 m0, s54
	s_nop 0
	s_add_u32 s98, s100, s16
	s_addc_u32 s99, s101, s17
	global_load_lds_dwordx4 v158, s[98:99]
	s_mov_b32 m0, s55
	s_nop 0
	s_add_u32 s98, s100, s18
	s_addc_u32 s99, s101, s19
	global_load_lds_dwordx4 v158, s[98:99]
	s_waitcnt vmcnt(8)
	s_waitcnt lgkmcnt(0)
	s_barrier
	s_setprio 1
	s_waitcnt lgkmcnt(0)
	v_mfma_i32_16x16x64_i8 v[92:95], v[112:115], v[172:175], v[92:95]
	v_mfma_i32_16x16x64_i8 v[92:95], v[116:119], v[182:185], v[92:95]
	v_mfma_i32_16x16x64_i8 v[84:87], v[112:115], v[186:189], v[84:87]
	v_mfma_i32_16x16x64_i8 v[84:87], v[116:119], v[190:193], v[84:87]
	v_mfma_i32_16x16x64_i8 v[76:79], v[112:115], v[194:197], v[76:79]
	v_mfma_i32_16x16x64_i8 v[76:79], v[116:119], v[198:201], v[76:79]
	v_mfma_i32_16x16x64_i8 v[68:71], v[112:115], v[206:209], v[68:71]
	v_mfma_i32_16x16x64_i8 v[68:71], v[116:119], v[210:213], v[68:71]
	v_mfma_i32_16x16x64_i8 v[64:67], v[128:131], v[206:209], v[64:67]
	v_mfma_i32_16x16x64_i8 v[64:67], v[142:145], v[210:213], v[64:67]
	v_mfma_i32_16x16x64_i8 v[72:75], v[128:131], v[194:197], v[72:75]
	v_mfma_i32_16x16x64_i8 v[72:75], v[142:145], v[198:201], v[72:75]
	v_mfma_i32_16x16x64_i8 v[80:83], v[128:131], v[186:189], v[80:83]
	v_mfma_i32_16x16x64_i8 v[80:83], v[142:145], v[190:193], v[80:83]
	v_mfma_i32_16x16x64_i8 v[88:91], v[128:131], v[172:175], v[88:91]
	v_mfma_i32_16x16x64_i8 v[88:91], v[142:145], v[182:185], v[88:91]
	s_setprio 0
	s_setprio 1
	v_mfma_i32_16x16x64_i8 v[28:31], v[146:149], v[172:175], v[28:31]
	v_mfma_i32_16x16x64_i8 v[28:31], v[150:153], v[182:185], v[28:31]
	v_mfma_i32_16x16x64_i8 v[20:23], v[146:149], v[186:189], v[20:23]
	v_mfma_i32_16x16x64_i8 v[20:23], v[150:153], v[190:193], v[20:23]
	v_mfma_i32_16x16x64_i8 v[12:15], v[146:149], v[194:197], v[12:15]
	v_mfma_i32_16x16x64_i8 v[12:15], v[150:153], v[198:201], v[12:15]
	v_mfma_i32_16x16x64_i8 v[4:7], v[146:149], v[206:209], v[4:7]
	v_mfma_i32_16x16x64_i8 v[4:7], v[150:153], v[210:213], v[4:7]
	v_mfma_i32_16x16x64_i8 v[0:3], v[154:157], v[206:209], v[0:3]
	v_mfma_i32_16x16x64_i8 v[0:3], v[168:171], v[210:213], v[0:3]
	v_mfma_i32_16x16x64_i8 v[8:11], v[154:157], v[194:197], v[8:11]
	v_mfma_i32_16x16x64_i8 v[8:11], v[168:171], v[198:201], v[8:11]
	s_setprio 2
	s_barrier
	v_mfma_i32_16x16x64_i8 v[16:19], v[154:157], v[186:189], v[16:19]
	v_mfma_i32_16x16x64_i8 v[16:19], v[168:171], v[190:193], v[16:19]
	v_mfma_i32_16x16x64_i8 v[24:27], v[154:157], v[172:175], v[24:27]
	v_mfma_i32_16x16x64_i8 v[24:27], v[168:171], v[182:185], v[24:27]
	s_setprio 0
	s_add_i32 s48, s48, 2
	s_add_u32 s68, s68, 0x100
	s_addc_u32 s69, s69, 0
	s_add_u32 s46, s46, 0x100
	s_addc_u32 s47, s47, 0
	s_cmp_gt_u32 s48, 29
	s_cbranch_scc0 .LBB0_1180
	s_and_b64 vcc, exec, s[34:35]
	s_cbranch_vccz .LBB0_1183
	s_barrier
